# FFN-down epilogue register copies as packed 64-bit moves (158 pairs)
# baseline (speedup 1.0000x reference)
; DI float bperm(float v, int srclane) { return __int_as_float(__builtin_amdgcn_ds_bpermute(srclane << 2, __float_as_int(v))); }
; DI u32x4 pack8(const float (&v)[8]) { u32x4 w; w.x = pk2(v[0], v[1]); w.y = pk2(v[2], v[3]); w.z = pk2(v[4], v[5]); w.w = pk2(v[6], v[7]); return w; }
; DI void row_stats(const float* STAT, int row, int fq, int lane, float& mu, float& rstd) {
;     const f32x4 a = *(const f32x4*)(STAT + (size_t)row * 32 + fq * 8), b = *(const f32x4*)(STAT + (size_t)row * 32 + fq * 8 + 4);
;     float s = (a[0] + a[2]) + (b[0] + b[2]), q = (a[1] + a[3]) + (b[1] + b[3]);
;     s += bperm(s, lane ^ 16); q += bperm(q, lane ^ 16); s += bperm(s, lane ^ 32); q += bperm(q, lane ^ 32);
;     mu = s * (1.0f / 1024.0f); rstd = __builtin_amdgcn_rsqf(fmaxf(q * (1.0f / 1024.0f) - mu * mu, 0.f) + EPS);
;     DI void operator()(const f32x4 (&acc)[2][2][4][2], const pg8::Unit& u, int wr, int wc, int fr, int fq) const {
;         asm volatile("" : "+v"(fr), "+v"(fq));
;         const int row0 = u.pm * 256 + wr * 64 + fr, col0 = u.pn * 256 + wc * 32 + 8 * fq, lane = fq * 16 + fr;
; #pragma unroll
;         for (int ai = 0; ai < 2; ++ai)
; #pragma unroll
;             for (int m = 0; m < 4; ++m) { const int row = row0 + ai * 128 + m * 16; const size_t off = (size_t)row * DMODEL + col0; float mu, rstd; row_stats(STAT, row, fq, lane, mu, rstd);
; #pragma unroll
;                 for (int bj = 0; bj < 2; ++bj) { float p[8]; unpack8(*(const u32x4*)(XBin + off + bj * 128), p);
;                     const f32x4 g0 = *(const f32x4*)(g + col0 + bj * 128), g1 = *(const f32x4*)(g + col0 + bj * 128 + 4), b0 = *(const f32x4*)(b + col0 + bj * 128), b1 = *(const f32x4*)(b + col0 + bj * 128 + 4);
;                     float o[8];
; #pragma unroll
;                     for (int k = 0; k < 8; ++k) { const float gg = k < 4 ? g0[k & 3] : g1[k & 3], bb = k < 4 ? b0[k & 3] : b1[k & 3]; const float x1 = (p[k] - mu) * rstd * gg + bb; o[k] = x1 * ALPHA + acc[ai][bj][m][k >> 2][k & 3]; }
;                     if (out32) { *(f32x4*)(out32 + off + bj * 128) = (f32x4){o[0], o[1], o[2], o[3]}; *(f32x4*)(out32 + off + bj * 128 + 4) = (f32x4){o[4], o[5], o[6], o[7]}; }
;                     else *(u32x4*)(XBout + off + bj * 128) = pack8(o); }
.LBB0_1979:
	s_lshl_b32 s2, s95, 8
	v_mov_b32_e32 v140, v159
	v_mov_b32_e32 v141, v158
	s_add_i32 s2, s2, s58
	s_andn2_b64 vcc, exec, s[44:45]
	v_add_u32_e32 v146, s2, v141
	s_lshl_b32 s2, s15, 8
	s_or_b32 s2, s2, s82
	v_lshlrev_b32_e32 v144, 3, v140
	v_lshlrev_b32_e32 v141, 2, v141
	v_add_u32_e32 v148, s2, v144
	v_lshl_add_u32 v140, v140, 6, v141
	v_ashrrev_i32_e32 v147, 31, v146
	v_ashrrev_i32_e32 v149, 31, v148
	v_xor_b32_e32 v163, 64, v140
	v_xor_b32_e32 v162, 0x80, v140
	v_lshlrev_b64 v[140:141], 10, v[146:147]
	v_lshl_add_u64 v[156:157], v[140:141], 0, v[148:149]
	v_lshlrev_b64 v[140:141], 7, v[146:147]
	v_ashrrev_i32_e32 v145, 31, v144
	v_lshl_add_u64 v[140:141], s[36:37], 0, v[140:141]
	v_lshl_add_u64 v[150:151], v[144:145], 2, v[140:141]
	global_load_dwordx4 v[140:143], v[150:151], off offset:16
	s_nop 0
	global_load_dwordx4 v[150:153], v[150:151], off
	v_lshlrev_b64 v[184:185], 2, v[148:149]
	v_lshl_add_u64 v[182:183], s[20:21], 0, v[184:185]
	v_lshl_add_u64 v[184:185], s[22:23], 0, v[184:185]
	global_load_dwordx4 v[220:223], v[182:183], off offset:16
	global_load_dwordx4 v[224:227], v[182:183], off
	global_load_dwordx4 v[228:231], v[184:185], off offset:16
	global_load_dwordx4 v[232:235], v[184:185], off
	global_load_dwordx4 v[242:245], v[182:183], off offset:528
	global_load_dwordx4 v[246:249], v[182:183], off offset:512
	global_load_dwordx4 v[250:253], v[184:185], off offset:528
	global_load_dwordx2 v[240:241], v[184:185], off offset:512
	global_load_dwordx2 v[186:187], v[184:185], off offset:520
	s_mov_b32 s2, 0x3a800000
	v_cndmask_b32_e64 v147, 0, 1, s[44:45]
	v_cmp_ne_u32_e64 s[18:19], 1, v147
	s_waitcnt vmcnt(9)
	v_pk_add_f32 v[140:141], v[140:141], v[142:143]
	v_pk_add_f32 v[150:151], v[150:151], v[152:153]
	s_nop 0
	v_pk_add_f32 v[140:141], v[150:151], v[140:141]
	ds_bpermute_b32 v142, v163, v140
	ds_bpermute_b32 v143, v163, v141
	v_lshl_add_u64 v[150:151], v[156:157], 1, s[26:27]
	global_load_dwordx4 v[164:167], v[150:151], off
	global_load_dwordx4 v[236:239], v[150:151], off offset:256
	v_lshl_add_u64 v[156:157], v[156:157], 2, s[28:29]
	s_waitcnt lgkmcnt(0)
	v_pk_add_f32 v[140:141], v[140:141], v[142:143]
	ds_bpermute_b32 v142, v162, v140
	ds_bpermute_b32 v143, v162, v141
	s_waitcnt lgkmcnt(0)
	v_pk_add_f32 v[140:141], v[140:141], v[142:143]
	s_nop 0
	v_pk_mul_f32 v[152:153], v[140:141], s[2:3] op_sel_hi:[1,0]
	s_waitcnt vmcnt(0)
	v_lshlrev_b32_e32 v184, 16, v164
	v_fma_f32 v140, -v152, v152, v153
	v_max_f32_e32 v140, 0, v140
	v_add_f32_e32 v140, 0x3727c5ac, v140
	v_rsq_f32_e32 v154, v140
	v_lshlrev_b64 v[140:141], 2, v[148:149]
	v_lshl_add_u64 v[142:143], s[20:21], 0, v[140:141]
	v_lshl_add_u64 v[140:141], s[22:23], 0, v[140:141]
	s_nop 1
	v_pk_mov_b32 v[168:169], v[220:221], v[220:221] op_sel:[0,1]
	v_pk_mov_b32 v[170:171], v[222:223], v[222:223] op_sel:[0,1]
	v_pk_mov_b32 v[172:173], v[224:225], v[224:225] op_sel:[0,1]
	v_pk_mov_b32 v[174:175], v[226:227], v[226:227] op_sel:[0,1]
	v_pk_mov_b32 v[176:177], v[228:229], v[228:229] op_sel:[0,1]
	v_pk_mov_b32 v[178:179], v[230:231], v[230:231] op_sel:[0,1]
	v_pk_mov_b32 v[180:181], v[232:233], v[232:233] op_sel:[0,1]
	v_pk_mov_b32 v[182:183], v[234:235], v[234:235] op_sel:[0,1]
	v_and_b32_e32 v185, 0xffff0000, v164
	v_lshlrev_b32_e32 v164, 16, v165
	v_and_b32_e32 v165, 0xffff0000, v165
	v_pk_add_f32 v[164:165], v[164:165], v[152:153] op_sel_hi:[1,0] neg_lo:[0,1] neg_hi:[0,1]
	v_pk_add_f32 v[184:185], v[184:185], v[152:153] op_sel_hi:[1,0] neg_lo:[0,1] neg_hi:[0,1]
	v_pk_mul_f32 v[164:165], v[164:165], v[154:155] op_sel_hi:[1,0]
	v_pk_mul_f32 v[184:185], v[184:185], v[154:155] op_sel_hi:[1,0]
	s_waitcnt vmcnt(0)
	v_pk_fma_f32 v[164:165], v[174:175], v[164:165], v[182:183]
	s_nop 0
	v_pk_fma_f32 v[128:129], v[164:165], s[86:87], v[128:129] op_sel_hi:[1,0,1]
	v_lshlrev_b32_e32 v164, 16, v166
	v_and_b32_e32 v165, 0xffff0000, v166
	v_pk_add_f32 v[164:165], v[164:165], v[152:153] op_sel_hi:[1,0] neg_lo:[0,1] neg_hi:[0,1]
	v_pk_fma_f32 v[172:173], v[172:173], v[184:185], v[180:181]
	v_pk_mul_f32 v[164:165], v[164:165], v[154:155] op_sel_hi:[1,0]
	v_pk_fma_f32 v[126:127], v[172:173], s[86:87], v[126:127] op_sel_hi:[1,0,1]
	v_pk_fma_f32 v[164:165], v[168:169], v[164:165], v[176:177]
	s_nop 0
	v_pk_fma_f32 v[122:123], v[164:165], s[86:87], v[122:123] op_sel_hi:[1,0,1]
	v_lshlrev_b32_e32 v164, 16, v167
	v_and_b32_e32 v165, 0xffff0000, v167
	v_pk_add_f32 v[164:165], v[164:165], v[152:153] op_sel_hi:[1,0] neg_lo:[0,1] neg_hi:[0,1]
	s_nop 0
	v_pk_mul_f32 v[164:165], v[164:165], v[154:155] op_sel_hi:[1,0]
	s_nop 0
	v_pk_fma_f32 v[164:165], v[170:171], v[164:165], v[178:179]
	s_nop 0
	v_pk_fma_f32 v[124:125], v[164:165], s[86:87], v[124:125] op_sel_hi:[1,0,1]
	s_cbranch_vccnz .LBB0_1981
	s_mov_b64 s[2:3], 0
	global_store_dwordx4 v[156:157], v[126:129], off
	global_store_dwordx4 v[156:157], v[122:125], off offset:16
	s_branch .LBB0_1982

; DI u32x4 pack8(const float (&v)[8]) { u32x4 w; w.x = pk2(v[0], v[1]); w.y = pk2(v[2], v[3]); w.z = pk2(v[4], v[5]); w.w = pk2(v[6], v[7]); return w; }
;     DI void operator()(const f32x4 (&acc)[2][2][4][2], const pg8::Unit& u, int wr, int wc, int fr, int fq) const {
;     ...
;                 for (int bj = 0; bj < 2; ++bj) { float p[8]; unpack8(*(const u32x4*)(XBin + off + bj * 128), p);
;                     const f32x4 g0 = *(const f32x4*)(g + col0 + bj * 128), g1 = *(const f32x4*)(g + col0 + bj * 128 + 4), b0 = *(const f32x4*)(b + col0 + bj * 128), b1 = *(const f32x4*)(b + col0 + bj * 128 + 4);
;                     float o[8];
; #pragma unroll
;                     for (int k = 0; k < 8; ++k) { const float gg = k < 4 ? g0[k & 3] : g1[k & 3], bb = k < 4 ? b0[k & 3] : b1[k & 3]; const float x1 = (p[k] - mu) * rstd * gg + bb; o[k] = x1 * ALPHA + acc[ai][bj][m][k >> 2][k & 3]; }
;                     if (out32) { *(f32x4*)(out32 + off + bj * 128) = (f32x4){o[0], o[1], o[2], o[3]}; *(f32x4*)(out32 + off + bj * 128 + 4) = (f32x4){o[4], o[5], o[6], o[7]}; }
;                     else *(u32x4*)(XBout + off + bj * 128) = pack8(o); }
.LBB0_1984:
	s_nop 1
	v_pk_mov_b32 v[122:123], v[236:237], v[236:237] op_sel:[0,1]
	v_pk_mov_b32 v[124:125], v[238:239], v[238:239] op_sel:[0,1]
	s_nop 0
	s_nop 1
	v_pk_mov_b32 v[126:127], v[242:243], v[242:243] op_sel:[0,1]
	v_pk_mov_b32 v[128:129], v[244:245], v[244:245] op_sel:[0,1]
	v_pk_mov_b32 v[164:165], v[246:247], v[246:247] op_sel:[0,1]
	v_pk_mov_b32 v[166:167], v[248:249], v[248:249] op_sel:[0,1]
	v_pk_mov_b32 v[168:169], v[250:251], v[250:251] op_sel:[0,1]
	v_pk_mov_b32 v[170:171], v[252:253], v[252:253] op_sel:[0,1]
	v_pk_mov_b32 v[172:173], v[240:241], v[240:241] op_sel:[0,1]
	v_pk_mov_b32 v[174:175], v[186:187], v[186:187] op_sel:[0,1]
	v_mov_b32_e32 v153, v152
	v_mov_b32_e32 v155, v154
	s_and_b64 vcc, exec, s[18:19]
	s_nop 0
	v_lshlrev_b32_e32 v176, 16, v122
	v_and_b32_e32 v177, 0xffff0000, v122
	v_lshlrev_b32_e32 v122, 16, v123
	v_and_b32_e32 v123, 0xffff0000, v123
	v_pk_add_f32 v[122:123], v[122:123], v[152:153] neg_lo:[0,1] neg_hi:[0,1]
	v_pk_add_f32 v[176:177], v[176:177], v[152:153] neg_lo:[0,1] neg_hi:[0,1]
	v_pk_mul_f32 v[122:123], v[154:155], v[122:123]
	v_pk_mul_f32 v[176:177], v[154:155], v[176:177]
	s_nop 0
	v_pk_fma_f32 v[122:123], v[166:167], v[122:123], v[174:175]
	v_pk_fma_f32 v[164:165], v[164:165], v[176:177], v[172:173]
	v_pk_fma_f32 v[120:121], v[122:123], s[86:87], v[120:121] op_sel_hi:[1,0,1]
	v_lshlrev_b32_e32 v122, 16, v124
	v_and_b32_e32 v123, 0xffff0000, v124
	v_pk_add_f32 v[122:123], v[122:123], v[152:153] neg_lo:[0,1] neg_hi:[0,1]
	v_pk_fma_f32 v[118:119], v[164:165], s[86:87], v[118:119] op_sel_hi:[1,0,1]
	v_pk_mul_f32 v[122:123], v[154:155], v[122:123]
	s_nop 0
	v_pk_fma_f32 v[122:123], v[126:127], v[122:123], v[168:169]
	s_nop 0
	v_pk_fma_f32 v[114:115], v[122:123], s[86:87], v[114:115] op_sel_hi:[1,0,1]
	v_lshlrev_b32_e32 v122, 16, v125
	v_and_b32_e32 v123, 0xffff0000, v125
	v_pk_add_f32 v[122:123], v[122:123], v[152:153] neg_lo:[0,1] neg_hi:[0,1]
	s_nop 0
	v_pk_mul_f32 v[122:123], v[154:155], v[122:123]
	s_nop 0
	v_pk_fma_f32 v[122:123], v[128:129], v[122:123], v[170:171]
	s_nop 0
	v_pk_fma_f32 v[116:117], v[122:123], s[86:87], v[116:117] op_sel_hi:[1,0,1]
	s_cbranch_vccnz .LBB0_2032
	global_store_dwordx4 v[156:157], v[118:121], off offset:512
	global_store_dwordx4 v[156:157], v[114:117], off offset:528
	s_cbranch_execnz .LBB0_1987

; DI float bperm(float v, int srclane) { return __int_as_float(__builtin_amdgcn_ds_bpermute(srclane << 2, __float_as_int(v))); }
; DI u32x4 pack8(const float (&v)[8]) { u32x4 w; w.x = pk2(v[0], v[1]); w.y = pk2(v[2], v[3]); w.z = pk2(v[4], v[5]); w.w = pk2(v[6], v[7]); return w; }
; DI void row_stats(const float* STAT, int row, int fq, int lane, float& mu, float& rstd) {
;     const f32x4 a = *(const f32x4*)(STAT + (size_t)row * 32 + fq * 8), b = *(const f32x4*)(STAT + (size_t)row * 32 + fq * 8 + 4);
;     float s = (a[0] + a[2]) + (b[0] + b[2]), q = (a[1] + a[3]) + (b[1] + b[3]);
;     s += bperm(s, lane ^ 16); q += bperm(q, lane ^ 16); s += bperm(s, lane ^ 32); q += bperm(q, lane ^ 32);
;     mu = s * (1.0f / 1024.0f); rstd = __builtin_amdgcn_rsqf(fmaxf(q * (1.0f / 1024.0f) - mu * mu, 0.f) + EPS);
;     DI void operator()(const f32x4 (&acc)[2][2][4][2], const pg8::Unit& u, int wr, int wc, int fr, int fq) const {
;     ...
;             for (int m = 0; m < 4; ++m) { const int row = row0 + ai * 128 + m * 16; const size_t off = (size_t)row * DMODEL + col0; float mu, rstd; row_stats(STAT, row, fq, lane, mu, rstd);
; #pragma unroll
;                 for (int bj = 0; bj < 2; ++bj) { float p[8]; unpack8(*(const u32x4*)(XBin + off + bj * 128), p);
;                     const f32x4 g0 = *(const f32x4*)(g + col0 + bj * 128), g1 = *(const f32x4*)(g + col0 + bj * 128 + 4), b0 = *(const f32x4*)(b + col0 + bj * 128), b1 = *(const f32x4*)(b + col0 + bj * 128 + 4);
;                     float o[8];
; #pragma unroll
;                     for (int k = 0; k < 8; ++k) { const float gg = k < 4 ? g0[k & 3] : g1[k & 3], bb = k < 4 ? b0[k & 3] : b1[k & 3]; const float x1 = (p[k] - mu) * rstd * gg + bb; o[k] = x1 * ALPHA + acc[ai][bj][m][k >> 2][k & 3]; }
;                     if (out32) { *(f32x4*)(out32 + off + bj * 128) = (f32x4){o[0], o[1], o[2], o[3]}; *(f32x4*)(out32 + off + bj * 128 + 4) = (f32x4){o[4], o[5], o[6], o[7]}; }
;                     else *(u32x4*)(XBout + off + bj * 128) = pack8(o); }
.LBB0_1987:
	s_nop 0
	v_add_u32_e32 v114, 16, v146
	v_ashrrev_i32_e32 v115, 31, v114
	v_lshlrev_b64 v[116:117], 10, v[114:115]
	v_lshlrev_b64 v[114:115], 7, v[114:115]
	v_lshl_add_u64 v[114:115], s[36:37], 0, v[114:115]
	v_lshl_add_u64 v[118:119], v[144:145], 2, v[114:115]
	s_nop 1
	v_pk_mov_b32 v[122:123], v[220:221], v[220:221] op_sel:[0,1]
	v_pk_mov_b32 v[124:125], v[222:223], v[222:223] op_sel:[0,1]
	v_pk_mov_b32 v[126:127], v[224:225], v[224:225] op_sel:[0,1]
	v_pk_mov_b32 v[128:129], v[226:227], v[226:227] op_sel:[0,1]
	v_pk_mov_b32 v[150:151], v[228:229], v[228:229] op_sel:[0,1]
	v_pk_mov_b32 v[152:153], v[230:231], v[230:231] op_sel:[0,1]
	v_pk_mov_b32 v[154:155], v[232:233], v[232:233] op_sel:[0,1]
	v_pk_mov_b32 v[156:157], v[234:235], v[234:235] op_sel:[0,1]
	v_lshl_add_u64 v[120:121], v[116:117], 0, v[148:149]
	global_load_dwordx4 v[114:117], v[118:119], off offset:16
	global_load_dwordx4 v[164:167], v[118:119], off
	v_lshl_add_u64 v[178:179], v[120:121], 1, s[26:27]
	global_load_dwordx4 v[170:173], v[178:179], off
	global_load_dwordx4 v[174:177], v[178:179], off offset:256
	s_mov_b32 s2, 0x3a800000
	s_and_b64 vcc, exec, s[18:19]
	s_waitcnt vmcnt(3)
	v_pk_add_f32 v[114:115], v[114:115], v[116:117]
	s_waitcnt vmcnt(2)
	v_pk_add_f32 v[118:119], v[164:165], v[166:167]
	s_nop 0
	v_pk_add_f32 v[114:115], v[118:119], v[114:115]
	ds_bpermute_b32 v116, v163, v114
	ds_bpermute_b32 v117, v163, v115
	s_waitcnt lgkmcnt(0)
	v_pk_add_f32 v[114:115], v[114:115], v[116:117]
	ds_bpermute_b32 v116, v162, v114
	ds_bpermute_b32 v117, v162, v115
	s_waitcnt lgkmcnt(0)
	v_pk_add_f32 v[114:115], v[114:115], v[116:117]
	s_nop 0
	v_pk_mul_f32 v[116:117], v[114:115], s[2:3] op_sel_hi:[1,0]
	s_nop 0
	v_fma_f32 v114, -v116, v116, v117
	v_max_f32_e32 v114, 0, v114
	v_add_f32_e32 v114, 0x3727c5ac, v114
	v_rsq_f32_e32 v118, v114
	v_lshl_add_u64 v[114:115], v[120:121], 1, s[26:27]
	s_waitcnt vmcnt(0)
	v_pk_mov_b32 v[164:165], v[170:171], v[170:171] op_sel:[0,1]
	v_pk_mov_b32 v[166:167], v[172:173], v[172:173] op_sel:[0,1]
	v_lshl_add_u64 v[120:121], v[120:121], 2, s[28:29]
	s_waitcnt vmcnt(0)
	v_lshlrev_b32_e32 v168, 16, v164
	v_and_b32_e32 v169, 0xffff0000, v164
	v_pk_add_f32 v[168:169], v[168:169], v[116:117] op_sel_hi:[1,0] neg_lo:[0,1] neg_hi:[0,1]
	s_nop 0
	v_pk_mul_f32 v[168:169], v[168:169], v[118:119] op_sel_hi:[1,0]
	s_nop 0
	v_pk_fma_f32 v[126:127], v[126:127], v[168:169], v[154:155]
	s_nop 0
	v_pk_fma_f32 v[110:111], v[126:127], s[86:87], v[110:111] op_sel_hi:[1,0,1]
	v_lshlrev_b32_e32 v126, 16, v165
	v_and_b32_e32 v127, 0xffff0000, v165
	v_pk_add_f32 v[126:127], v[126:127], v[116:117] op_sel_hi:[1,0] neg_lo:[0,1] neg_hi:[0,1]
	s_nop 0
	v_pk_mul_f32 v[126:127], v[126:127], v[118:119] op_sel_hi:[1,0]
	s_nop 0
	v_pk_fma_f32 v[126:127], v[128:129], v[126:127], v[156:157]
	s_nop 0
	v_pk_fma_f32 v[112:113], v[126:127], s[86:87], v[112:113] op_sel_hi:[1,0,1]
	v_lshlrev_b32_e32 v126, 16, v166
	v_and_b32_e32 v127, 0xffff0000, v166
	v_pk_add_f32 v[126:127], v[126:127], v[116:117] op_sel_hi:[1,0] neg_lo:[0,1] neg_hi:[0,1]
	s_nop 0
	v_pk_mul_f32 v[126:127], v[126:127], v[118:119] op_sel_hi:[1,0]
	s_nop 0
	v_pk_fma_f32 v[122:123], v[122:123], v[126:127], v[150:151]
	s_nop 0
	v_pk_fma_f32 v[106:107], v[122:123], s[86:87], v[106:107] op_sel_hi:[1,0,1]
	v_lshlrev_b32_e32 v122, 16, v167
	v_and_b32_e32 v123, 0xffff0000, v167
	v_pk_add_f32 v[122:123], v[122:123], v[116:117] op_sel_hi:[1,0] neg_lo:[0,1] neg_hi:[0,1]
	s_nop 0
	v_pk_mul_f32 v[122:123], v[122:123], v[118:119] op_sel_hi:[1,0]
	s_nop 0
	v_pk_fma_f32 v[122:123], v[124:125], v[122:123], v[152:153]
	s_nop 0
	v_pk_fma_f32 v[108:109], v[122:123], s[86:87], v[108:109] op_sel_hi:[1,0,1]
	s_cbranch_vccnz .LBB0_2033
	global_store_dwordx4 v[120:121], v[110:113], off
	global_store_dwordx4 v[120:121], v[106:109], off offset:16
	s_cbranch_execnz .LBB0_1990

; DI u32x4 pack8(const float (&v)[8]) { u32x4 w; w.x = pk2(v[0], v[1]); w.y = pk2(v[2], v[3]); w.z = pk2(v[4], v[5]); w.w = pk2(v[6], v[7]); return w; }
;     DI void operator()(const f32x4 (&acc)[2][2][4][2], const pg8::Unit& u, int wr, int wc, int fr, int fq) const {
;     ...
;                 for (int bj = 0; bj < 2; ++bj) { float p[8]; unpack8(*(const u32x4*)(XBin + off + bj * 128), p);
;                     const f32x4 g0 = *(const f32x4*)(g + col0 + bj * 128), g1 = *(const f32x4*)(g + col0 + bj * 128 + 4), b0 = *(const f32x4*)(b + col0 + bj * 128), b1 = *(const f32x4*)(b + col0 + bj * 128 + 4);
;                     float o[8];
; #pragma unroll
;                     for (int k = 0; k < 8; ++k) { const float gg = k < 4 ? g0[k & 3] : g1[k & 3], bb = k < 4 ? b0[k & 3] : b1[k & 3]; const float x1 = (p[k] - mu) * rstd * gg + bb; o[k] = x1 * ALPHA + acc[ai][bj][m][k >> 2][k & 3]; }
;                     if (out32) { *(f32x4*)(out32 + off + bj * 128) = (f32x4){o[0], o[1], o[2], o[3]}; *(f32x4*)(out32 + off + bj * 128 + 4) = (f32x4){o[4], o[5], o[6], o[7]}; }
;                     else *(u32x4*)(XBout + off + bj * 128) = pack8(o); }
.LBB0_1990:
	s_nop 1
	v_pk_mov_b32 v[106:107], v[174:175], v[174:175] op_sel:[0,1]
	v_pk_mov_b32 v[108:109], v[176:177], v[176:177] op_sel:[0,1]
	s_nop 0
	s_nop 1
	v_pk_mov_b32 v[110:111], v[242:243], v[242:243] op_sel:[0,1]
	v_pk_mov_b32 v[112:113], v[244:245], v[244:245] op_sel:[0,1]
	v_pk_mov_b32 v[122:123], v[246:247], v[246:247] op_sel:[0,1]
	v_pk_mov_b32 v[124:125], v[248:249], v[248:249] op_sel:[0,1]
	v_pk_mov_b32 v[126:127], v[250:251], v[250:251] op_sel:[0,1]
	v_pk_mov_b32 v[128:129], v[252:253], v[252:253] op_sel:[0,1]
	v_pk_mov_b32 v[150:151], v[240:241], v[240:241] op_sel:[0,1]
	v_pk_mov_b32 v[152:153], v[186:187], v[186:187] op_sel:[0,1]
	v_mov_b32_e32 v117, v116
	v_mov_b32_e32 v119, v118
	s_and_b64 vcc, exec, s[18:19]
	s_nop 0
	v_lshlrev_b32_e32 v154, 16, v106
	v_and_b32_e32 v155, 0xffff0000, v106
	v_lshlrev_b32_e32 v106, 16, v107
	v_and_b32_e32 v107, 0xffff0000, v107
	v_pk_add_f32 v[106:107], v[106:107], v[116:117] neg_lo:[0,1] neg_hi:[0,1]
	v_pk_add_f32 v[154:155], v[154:155], v[116:117] neg_lo:[0,1] neg_hi:[0,1]
	v_pk_mul_f32 v[106:107], v[118:119], v[106:107]
	v_pk_mul_f32 v[154:155], v[118:119], v[154:155]
	s_nop 0
	v_pk_fma_f32 v[106:107], v[124:125], v[106:107], v[152:153]
	v_pk_fma_f32 v[122:123], v[122:123], v[154:155], v[150:151]
	v_pk_fma_f32 v[104:105], v[106:107], s[86:87], v[104:105] op_sel_hi:[1,0,1]
	v_lshlrev_b32_e32 v106, 16, v108
	v_and_b32_e32 v107, 0xffff0000, v108
	v_pk_add_f32 v[106:107], v[106:107], v[116:117] neg_lo:[0,1] neg_hi:[0,1]
	v_pk_fma_f32 v[102:103], v[122:123], s[86:87], v[102:103] op_sel_hi:[1,0,1]
	v_pk_mul_f32 v[106:107], v[118:119], v[106:107]
	s_nop 0
	v_pk_fma_f32 v[106:107], v[110:111], v[106:107], v[126:127]
	s_nop 0
	v_pk_fma_f32 v[98:99], v[106:107], s[86:87], v[98:99] op_sel_hi:[1,0,1]
	v_lshlrev_b32_e32 v106, 16, v109
	v_and_b32_e32 v107, 0xffff0000, v109
	v_pk_add_f32 v[106:107], v[106:107], v[116:117] neg_lo:[0,1] neg_hi:[0,1]
	s_nop 0
	v_pk_mul_f32 v[106:107], v[118:119], v[106:107]
	s_nop 0
	v_pk_fma_f32 v[106:107], v[112:113], v[106:107], v[128:129]
	s_nop 0
	v_pk_fma_f32 v[100:101], v[106:107], s[86:87], v[100:101] op_sel_hi:[1,0,1]
	s_cbranch_vccnz .LBB0_2034
	global_store_dwordx4 v[120:121], v[102:105], off offset:512
	global_store_dwordx4 v[120:121], v[98:101], off offset:528
	s_cbranch_execnz .LBB0_1993

; DI float bperm(float v, int srclane) { return __int_as_float(__builtin_amdgcn_ds_bpermute(srclane << 2, __float_as_int(v))); }
; DI u32x4 pack8(const float (&v)[8]) { u32x4 w; w.x = pk2(v[0], v[1]); w.y = pk2(v[2], v[3]); w.z = pk2(v[4], v[5]); w.w = pk2(v[6], v[7]); return w; }
; DI void row_stats(const float* STAT, int row, int fq, int lane, float& mu, float& rstd) {
;     const f32x4 a = *(const f32x4*)(STAT + (size_t)row * 32 + fq * 8), b = *(const f32x4*)(STAT + (size_t)row * 32 + fq * 8 + 4);
;     float s = (a[0] + a[2]) + (b[0] + b[2]), q = (a[1] + a[3]) + (b[1] + b[3]);
;     s += bperm(s, lane ^ 16); q += bperm(q, lane ^ 16); s += bperm(s, lane ^ 32); q += bperm(q, lane ^ 32);
;     mu = s * (1.0f / 1024.0f); rstd = __builtin_amdgcn_rsqf(fmaxf(q * (1.0f / 1024.0f) - mu * mu, 0.f) + EPS);
;     DI void operator()(const f32x4 (&acc)[2][2][4][2], const pg8::Unit& u, int wr, int wc, int fr, int fq) const {
;     ...
;             for (int m = 0; m < 4; ++m) { const int row = row0 + ai * 128 + m * 16; const size_t off = (size_t)row * DMODEL + col0; float mu, rstd; row_stats(STAT, row, fq, lane, mu, rstd);
; #pragma unroll
;                 for (int bj = 0; bj < 2; ++bj) { float p[8]; unpack8(*(const u32x4*)(XBin + off + bj * 128), p);
;                     const f32x4 g0 = *(const f32x4*)(g + col0 + bj * 128), g1 = *(const f32x4*)(g + col0 + bj * 128 + 4), b0 = *(const f32x4*)(b + col0 + bj * 128), b1 = *(const f32x4*)(b + col0 + bj * 128 + 4);
;                     float o[8];
; #pragma unroll
;                     for (int k = 0; k < 8; ++k) { const float gg = k < 4 ? g0[k & 3] : g1[k & 3], bb = k < 4 ? b0[k & 3] : b1[k & 3]; const float x1 = (p[k] - mu) * rstd * gg + bb; o[k] = x1 * ALPHA + acc[ai][bj][m][k >> 2][k & 3]; }
;                     if (out32) { *(f32x4*)(out32 + off + bj * 128) = (f32x4){o[0], o[1], o[2], o[3]}; *(f32x4*)(out32 + off + bj * 128 + 4) = (f32x4){o[4], o[5], o[6], o[7]}; }
;                     else *(u32x4*)(XBout + off + bj * 128) = pack8(o); }
.LBB0_1993:
	s_nop 0
	v_add_u32_e32 v98, 32, v146
	v_ashrrev_i32_e32 v99, 31, v98
	v_lshlrev_b64 v[100:101], 10, v[98:99]
	v_lshlrev_b64 v[98:99], 7, v[98:99]
	v_lshl_add_u64 v[98:99], s[36:37], 0, v[98:99]
	v_lshl_add_u64 v[102:103], v[144:145], 2, v[98:99]
	s_nop 1
	v_pk_mov_b32 v[106:107], v[220:221], v[220:221] op_sel:[0,1]
	v_pk_mov_b32 v[108:109], v[222:223], v[222:223] op_sel:[0,1]
	v_pk_mov_b32 v[110:111], v[224:225], v[224:225] op_sel:[0,1]
	v_pk_mov_b32 v[112:113], v[226:227], v[226:227] op_sel:[0,1]
	v_pk_mov_b32 v[114:115], v[228:229], v[228:229] op_sel:[0,1]
	v_pk_mov_b32 v[116:117], v[230:231], v[230:231] op_sel:[0,1]
	v_pk_mov_b32 v[118:119], v[232:233], v[232:233] op_sel:[0,1]
	v_pk_mov_b32 v[120:121], v[234:235], v[234:235] op_sel:[0,1]
	v_lshl_add_u64 v[104:105], v[100:101], 0, v[148:149]
	global_load_dwordx4 v[98:101], v[102:103], off offset:16
	global_load_dwordx4 v[122:125], v[102:103], off
	v_lshl_add_u64 v[178:179], v[104:105], 1, s[26:27]
	global_load_dwordx4 v[170:173], v[178:179], off
	global_load_dwordx4 v[174:177], v[178:179], off offset:256
	s_mov_b32 s2, 0x3a800000
	s_and_b64 vcc, exec, s[18:19]
	s_waitcnt vmcnt(3)
	v_pk_add_f32 v[98:99], v[98:99], v[100:101]
	s_waitcnt vmcnt(2)
	v_pk_add_f32 v[102:103], v[122:123], v[124:125]
	s_nop 0
	v_pk_add_f32 v[98:99], v[102:103], v[98:99]
	ds_bpermute_b32 v100, v163, v98
	ds_bpermute_b32 v101, v163, v99
	s_waitcnt lgkmcnt(0)
	v_pk_add_f32 v[98:99], v[98:99], v[100:101]
	ds_bpermute_b32 v100, v162, v98
	ds_bpermute_b32 v101, v162, v99
	s_waitcnt lgkmcnt(0)
	v_pk_add_f32 v[98:99], v[98:99], v[100:101]
	s_nop 0
	v_pk_mul_f32 v[100:101], v[98:99], s[2:3] op_sel_hi:[1,0]
	s_nop 0
	v_fma_f32 v98, -v100, v100, v101
	v_max_f32_e32 v98, 0, v98
	v_add_f32_e32 v98, 0x3727c5ac, v98
	v_rsq_f32_e32 v102, v98
	v_lshl_add_u64 v[98:99], v[104:105], 1, s[26:27]
	s_waitcnt vmcnt(0)
	v_pk_mov_b32 v[122:123], v[170:171], v[170:171] op_sel:[0,1]
	v_pk_mov_b32 v[124:125], v[172:173], v[172:173] op_sel:[0,1]
	v_lshl_add_u64 v[104:105], v[104:105], 2, s[28:29]
	s_waitcnt vmcnt(0)
	v_lshlrev_b32_e32 v126, 16, v122
	v_and_b32_e32 v127, 0xffff0000, v122
	v_pk_add_f32 v[126:127], v[126:127], v[100:101] op_sel_hi:[1,0] neg_lo:[0,1] neg_hi:[0,1]
	s_nop 0
	v_pk_mul_f32 v[126:127], v[126:127], v[102:103] op_sel_hi:[1,0]
	s_nop 0
	v_pk_fma_f32 v[110:111], v[110:111], v[126:127], v[118:119]
	s_nop 0
	v_pk_fma_f32 v[94:95], v[110:111], s[86:87], v[94:95] op_sel_hi:[1,0,1]
	v_lshlrev_b32_e32 v110, 16, v123
	v_and_b32_e32 v111, 0xffff0000, v123
	v_pk_add_f32 v[110:111], v[110:111], v[100:101] op_sel_hi:[1,0] neg_lo:[0,1] neg_hi:[0,1]
	s_nop 0
	v_pk_mul_f32 v[110:111], v[110:111], v[102:103] op_sel_hi:[1,0]
	s_nop 0
	v_pk_fma_f32 v[110:111], v[112:113], v[110:111], v[120:121]
	s_nop 0
	v_pk_fma_f32 v[96:97], v[110:111], s[86:87], v[96:97] op_sel_hi:[1,0,1]
	v_lshlrev_b32_e32 v110, 16, v124
	v_and_b32_e32 v111, 0xffff0000, v124
	v_pk_add_f32 v[110:111], v[110:111], v[100:101] op_sel_hi:[1,0] neg_lo:[0,1] neg_hi:[0,1]
	s_nop 0
	v_pk_mul_f32 v[110:111], v[110:111], v[102:103] op_sel_hi:[1,0]
	s_nop 0
	v_pk_fma_f32 v[106:107], v[106:107], v[110:111], v[114:115]
	s_nop 0
	v_pk_fma_f32 v[90:91], v[106:107], s[86:87], v[90:91] op_sel_hi:[1,0,1]
	v_lshlrev_b32_e32 v106, 16, v125
	v_and_b32_e32 v107, 0xffff0000, v125
	v_pk_add_f32 v[106:107], v[106:107], v[100:101] op_sel_hi:[1,0] neg_lo:[0,1] neg_hi:[0,1]
	s_nop 0
	v_pk_mul_f32 v[106:107], v[106:107], v[102:103] op_sel_hi:[1,0]
	s_nop 0
	v_pk_fma_f32 v[106:107], v[108:109], v[106:107], v[116:117]
	s_nop 0
	v_pk_fma_f32 v[92:93], v[106:107], s[86:87], v[92:93] op_sel_hi:[1,0,1]
	s_cbranch_vccnz .LBB0_2035
	global_store_dwordx4 v[104:105], v[94:97], off
	global_store_dwordx4 v[104:105], v[90:93], off offset:16
	s_cbranch_execnz .LBB0_1996

; DI u32x4 pack8(const float (&v)[8]) { u32x4 w; w.x = pk2(v[0], v[1]); w.y = pk2(v[2], v[3]); w.z = pk2(v[4], v[5]); w.w = pk2(v[6], v[7]); return w; }
;     DI void operator()(const f32x4 (&acc)[2][2][4][2], const pg8::Unit& u, int wr, int wc, int fr, int fq) const {
;     ...
;                 for (int bj = 0; bj < 2; ++bj) { float p[8]; unpack8(*(const u32x4*)(XBin + off + bj * 128), p);
;                     const f32x4 g0 = *(const f32x4*)(g + col0 + bj * 128), g1 = *(const f32x4*)(g + col0 + bj * 128 + 4), b0 = *(const f32x4*)(b + col0 + bj * 128), b1 = *(const f32x4*)(b + col0 + bj * 128 + 4);
;                     float o[8];
; #pragma unroll
;                     for (int k = 0; k < 8; ++k) { const float gg = k < 4 ? g0[k & 3] : g1[k & 3], bb = k < 4 ? b0[k & 3] : b1[k & 3]; const float x1 = (p[k] - mu) * rstd * gg + bb; o[k] = x1 * ALPHA + acc[ai][bj][m][k >> 2][k & 3]; }
;                     if (out32) { *(f32x4*)(out32 + off + bj * 128) = (f32x4){o[0], o[1], o[2], o[3]}; *(f32x4*)(out32 + off + bj * 128 + 4) = (f32x4){o[4], o[5], o[6], o[7]}; }
;                     else *(u32x4*)(XBout + off + bj * 128) = pack8(o); }
.LBB0_1996:
	s_nop 1
	v_pk_mov_b32 v[90:91], v[174:175], v[174:175] op_sel:[0,1]
	v_pk_mov_b32 v[92:93], v[176:177], v[176:177] op_sel:[0,1]
	s_nop 0
	s_nop 1
	v_pk_mov_b32 v[94:95], v[242:243], v[242:243] op_sel:[0,1]
	v_pk_mov_b32 v[96:97], v[244:245], v[244:245] op_sel:[0,1]
	v_pk_mov_b32 v[106:107], v[246:247], v[246:247] op_sel:[0,1]
	v_pk_mov_b32 v[108:109], v[248:249], v[248:249] op_sel:[0,1]
	v_pk_mov_b32 v[110:111], v[250:251], v[250:251] op_sel:[0,1]
	v_pk_mov_b32 v[112:113], v[252:253], v[252:253] op_sel:[0,1]
	v_pk_mov_b32 v[114:115], v[240:241], v[240:241] op_sel:[0,1]
	v_pk_mov_b32 v[116:117], v[186:187], v[186:187] op_sel:[0,1]
	v_mov_b32_e32 v101, v100
	v_mov_b32_e32 v103, v102
	s_and_b64 vcc, exec, s[18:19]
	s_nop 0
	v_lshlrev_b32_e32 v118, 16, v90
	v_and_b32_e32 v119, 0xffff0000, v90
	v_lshlrev_b32_e32 v90, 16, v91
	v_and_b32_e32 v91, 0xffff0000, v91
	v_pk_add_f32 v[90:91], v[90:91], v[100:101] neg_lo:[0,1] neg_hi:[0,1]
	v_pk_add_f32 v[118:119], v[118:119], v[100:101] neg_lo:[0,1] neg_hi:[0,1]
	v_pk_mul_f32 v[90:91], v[102:103], v[90:91]
	v_pk_mul_f32 v[118:119], v[102:103], v[118:119]
	s_nop 0
	v_pk_fma_f32 v[90:91], v[108:109], v[90:91], v[116:117]
	v_pk_fma_f32 v[106:107], v[106:107], v[118:119], v[114:115]
	v_pk_fma_f32 v[88:89], v[90:91], s[86:87], v[88:89] op_sel_hi:[1,0,1]
	v_lshlrev_b32_e32 v90, 16, v92
	v_and_b32_e32 v91, 0xffff0000, v92
	v_pk_add_f32 v[90:91], v[90:91], v[100:101] neg_lo:[0,1] neg_hi:[0,1]
	v_pk_fma_f32 v[86:87], v[106:107], s[86:87], v[86:87] op_sel_hi:[1,0,1]
	v_pk_mul_f32 v[90:91], v[102:103], v[90:91]
	s_nop 0
	v_pk_fma_f32 v[90:91], v[94:95], v[90:91], v[110:111]
	s_nop 0
	v_pk_fma_f32 v[82:83], v[90:91], s[86:87], v[82:83] op_sel_hi:[1,0,1]
	v_lshlrev_b32_e32 v90, 16, v93
	v_and_b32_e32 v91, 0xffff0000, v93
	v_pk_add_f32 v[90:91], v[90:91], v[100:101] neg_lo:[0,1] neg_hi:[0,1]
	s_nop 0
	v_pk_mul_f32 v[90:91], v[102:103], v[90:91]
	s_nop 0
	v_pk_fma_f32 v[90:91], v[96:97], v[90:91], v[112:113]
	s_nop 0
	v_pk_fma_f32 v[84:85], v[90:91], s[86:87], v[84:85] op_sel_hi:[1,0,1]
	s_cbranch_vccnz .LBB0_2036
	global_store_dwordx4 v[104:105], v[86:89], off offset:512
	global_store_dwordx4 v[104:105], v[82:85], off offset:528
	s_cbranch_execnz .LBB0_1999

; DI float bperm(float v, int srclane) { return __int_as_float(__builtin_amdgcn_ds_bpermute(srclane << 2, __float_as_int(v))); }
; DI u32x4 pack8(const float (&v)[8]) { u32x4 w; w.x = pk2(v[0], v[1]); w.y = pk2(v[2], v[3]); w.z = pk2(v[4], v[5]); w.w = pk2(v[6], v[7]); return w; }
; DI void row_stats(const float* STAT, int row, int fq, int lane, float& mu, float& rstd) {
;     const f32x4 a = *(const f32x4*)(STAT + (size_t)row * 32 + fq * 8), b = *(const f32x4*)(STAT + (size_t)row * 32 + fq * 8 + 4);
;     float s = (a[0] + a[2]) + (b[0] + b[2]), q = (a[1] + a[3]) + (b[1] + b[3]);
;     s += bperm(s, lane ^ 16); q += bperm(q, lane ^ 16); s += bperm(s, lane ^ 32); q += bperm(q, lane ^ 32);
;     mu = s * (1.0f / 1024.0f); rstd = __builtin_amdgcn_rsqf(fmaxf(q * (1.0f / 1024.0f) - mu * mu, 0.f) + EPS);
;     DI void operator()(const f32x4 (&acc)[2][2][4][2], const pg8::Unit& u, int wr, int wc, int fr, int fq) const {
;     ...
;             for (int m = 0; m < 4; ++m) { const int row = row0 + ai * 128 + m * 16; const size_t off = (size_t)row * DMODEL + col0; float mu, rstd; row_stats(STAT, row, fq, lane, mu, rstd);
; #pragma unroll
;                 for (int bj = 0; bj < 2; ++bj) { float p[8]; unpack8(*(const u32x4*)(XBin + off + bj * 128), p);
;                     const f32x4 g0 = *(const f32x4*)(g + col0 + bj * 128), g1 = *(const f32x4*)(g + col0 + bj * 128 + 4), b0 = *(const f32x4*)(b + col0 + bj * 128), b1 = *(const f32x4*)(b + col0 + bj * 128 + 4);
;                     float o[8];
; #pragma unroll
;                     for (int k = 0; k < 8; ++k) { const float gg = k < 4 ? g0[k & 3] : g1[k & 3], bb = k < 4 ? b0[k & 3] : b1[k & 3]; const float x1 = (p[k] - mu) * rstd * gg + bb; o[k] = x1 * ALPHA + acc[ai][bj][m][k >> 2][k & 3]; }
;                     if (out32) { *(f32x4*)(out32 + off + bj * 128) = (f32x4){o[0], o[1], o[2], o[3]}; *(f32x4*)(out32 + off + bj * 128 + 4) = (f32x4){o[4], o[5], o[6], o[7]}; }
;                     else *(u32x4*)(XBout + off + bj * 128) = pack8(o); }
.LBB0_1999:
	s_nop 0
	v_add_u32_e32 v82, 48, v146
	v_ashrrev_i32_e32 v83, 31, v82
	v_lshlrev_b64 v[84:85], 10, v[82:83]
	v_lshlrev_b64 v[82:83], 7, v[82:83]
	v_lshl_add_u64 v[82:83], s[36:37], 0, v[82:83]
	v_lshl_add_u64 v[86:87], v[144:145], 2, v[82:83]
	s_nop 1
	v_pk_mov_b32 v[90:91], v[220:221], v[220:221] op_sel:[0,1]
	v_pk_mov_b32 v[92:93], v[222:223], v[222:223] op_sel:[0,1]
	v_pk_mov_b32 v[94:95], v[224:225], v[224:225] op_sel:[0,1]
	v_pk_mov_b32 v[96:97], v[226:227], v[226:227] op_sel:[0,1]
	v_pk_mov_b32 v[98:99], v[228:229], v[228:229] op_sel:[0,1]
	v_pk_mov_b32 v[100:101], v[230:231], v[230:231] op_sel:[0,1]
	v_pk_mov_b32 v[102:103], v[232:233], v[232:233] op_sel:[0,1]
	v_pk_mov_b32 v[104:105], v[234:235], v[234:235] op_sel:[0,1]
	v_lshl_add_u64 v[88:89], v[84:85], 0, v[148:149]
	global_load_dwordx4 v[82:85], v[86:87], off offset:16
	global_load_dwordx4 v[106:109], v[86:87], off
	v_lshl_add_u64 v[178:179], v[88:89], 1, s[26:27]
	global_load_dwordx4 v[170:173], v[178:179], off
	global_load_dwordx4 v[174:177], v[178:179], off offset:256
	s_mov_b32 s2, 0x3a800000
	s_and_b64 vcc, exec, s[18:19]
	s_waitcnt vmcnt(3)
	v_pk_add_f32 v[82:83], v[82:83], v[84:85]
	s_waitcnt vmcnt(2)
	v_pk_add_f32 v[86:87], v[106:107], v[108:109]
	s_nop 0
	v_pk_add_f32 v[82:83], v[86:87], v[82:83]
	ds_bpermute_b32 v84, v163, v82
	ds_bpermute_b32 v85, v163, v83
	s_waitcnt lgkmcnt(0)
	v_pk_add_f32 v[82:83], v[82:83], v[84:85]
	ds_bpermute_b32 v84, v162, v82
	ds_bpermute_b32 v85, v162, v83
	s_waitcnt lgkmcnt(0)
	v_pk_add_f32 v[82:83], v[82:83], v[84:85]
	s_nop 0
	v_pk_mul_f32 v[84:85], v[82:83], s[2:3] op_sel_hi:[1,0]
	s_nop 0
	v_fma_f32 v82, -v84, v84, v85
	v_max_f32_e32 v82, 0, v82
	v_add_f32_e32 v82, 0x3727c5ac, v82
	v_rsq_f32_e32 v86, v82
	v_lshl_add_u64 v[82:83], v[88:89], 1, s[26:27]
	s_waitcnt vmcnt(0)
	v_pk_mov_b32 v[106:107], v[170:171], v[170:171] op_sel:[0,1]
	v_pk_mov_b32 v[108:109], v[172:173], v[172:173] op_sel:[0,1]
	v_lshl_add_u64 v[88:89], v[88:89], 2, s[28:29]
	s_waitcnt vmcnt(0)
	v_lshlrev_b32_e32 v110, 16, v106
	v_and_b32_e32 v111, 0xffff0000, v106
	v_pk_add_f32 v[110:111], v[110:111], v[84:85] op_sel_hi:[1,0] neg_lo:[0,1] neg_hi:[0,1]
	s_nop 0
	v_pk_mul_f32 v[110:111], v[110:111], v[86:87] op_sel_hi:[1,0]
	s_nop 0
	v_pk_fma_f32 v[94:95], v[94:95], v[110:111], v[102:103]
	s_nop 0
	v_pk_fma_f32 v[78:79], v[94:95], s[86:87], v[78:79] op_sel_hi:[1,0,1]
	v_lshlrev_b32_e32 v94, 16, v107
	v_and_b32_e32 v95, 0xffff0000, v107
	v_pk_add_f32 v[94:95], v[94:95], v[84:85] op_sel_hi:[1,0] neg_lo:[0,1] neg_hi:[0,1]
	s_nop 0
	v_pk_mul_f32 v[94:95], v[94:95], v[86:87] op_sel_hi:[1,0]
	s_nop 0
	v_pk_fma_f32 v[94:95], v[96:97], v[94:95], v[104:105]
	s_nop 0
	v_pk_fma_f32 v[80:81], v[94:95], s[86:87], v[80:81] op_sel_hi:[1,0,1]
	v_lshlrev_b32_e32 v94, 16, v108
	v_and_b32_e32 v95, 0xffff0000, v108
	v_pk_add_f32 v[94:95], v[94:95], v[84:85] op_sel_hi:[1,0] neg_lo:[0,1] neg_hi:[0,1]
	s_nop 0
	v_pk_mul_f32 v[94:95], v[94:95], v[86:87] op_sel_hi:[1,0]
	s_nop 0
	v_pk_fma_f32 v[90:91], v[90:91], v[94:95], v[98:99]
	s_nop 0
	v_pk_fma_f32 v[74:75], v[90:91], s[86:87], v[74:75] op_sel_hi:[1,0,1]
	v_lshlrev_b32_e32 v90, 16, v109
	v_and_b32_e32 v91, 0xffff0000, v109
	v_pk_add_f32 v[90:91], v[90:91], v[84:85] op_sel_hi:[1,0] neg_lo:[0,1] neg_hi:[0,1]
	s_nop 0
	v_pk_mul_f32 v[90:91], v[90:91], v[86:87] op_sel_hi:[1,0]
	s_nop 0
	v_pk_fma_f32 v[90:91], v[92:93], v[90:91], v[100:101]
	s_nop 0
	v_pk_fma_f32 v[76:77], v[90:91], s[86:87], v[76:77] op_sel_hi:[1,0,1]
	s_cbranch_vccnz .LBB0_2037
	global_store_dwordx4 v[88:89], v[78:81], off
	global_store_dwordx4 v[88:89], v[74:77], off offset:16
	s_cbranch_execnz .LBB0_2002

; DI u32x4 pack8(const float (&v)[8]) { u32x4 w; w.x = pk2(v[0], v[1]); w.y = pk2(v[2], v[3]); w.z = pk2(v[4], v[5]); w.w = pk2(v[6], v[7]); return w; }
;     DI void operator()(const f32x4 (&acc)[2][2][4][2], const pg8::Unit& u, int wr, int wc, int fr, int fq) const {
;     ...
;                 for (int bj = 0; bj < 2; ++bj) { float p[8]; unpack8(*(const u32x4*)(XBin + off + bj * 128), p);
;                     const f32x4 g0 = *(const f32x4*)(g + col0 + bj * 128), g1 = *(const f32x4*)(g + col0 + bj * 128 + 4), b0 = *(const f32x4*)(b + col0 + bj * 128), b1 = *(const f32x4*)(b + col0 + bj * 128 + 4);
;                     float o[8];
; #pragma unroll
;                     for (int k = 0; k < 8; ++k) { const float gg = k < 4 ? g0[k & 3] : g1[k & 3], bb = k < 4 ? b0[k & 3] : b1[k & 3]; const float x1 = (p[k] - mu) * rstd * gg + bb; o[k] = x1 * ALPHA + acc[ai][bj][m][k >> 2][k & 3]; }
;                     if (out32) { *(f32x4*)(out32 + off + bj * 128) = (f32x4){o[0], o[1], o[2], o[3]}; *(f32x4*)(out32 + off + bj * 128 + 4) = (f32x4){o[4], o[5], o[6], o[7]}; }
;                     else *(u32x4*)(XBout + off + bj * 128) = pack8(o); }
.LBB0_2002:
	s_nop 1
	v_pk_mov_b32 v[74:75], v[174:175], v[174:175] op_sel:[0,1]
	v_pk_mov_b32 v[76:77], v[176:177], v[176:177] op_sel:[0,1]
	s_nop 0
	s_nop 1
	v_pk_mov_b32 v[78:79], v[242:243], v[242:243] op_sel:[0,1]
	v_pk_mov_b32 v[80:81], v[244:245], v[244:245] op_sel:[0,1]
	v_pk_mov_b32 v[90:91], v[246:247], v[246:247] op_sel:[0,1]
	v_pk_mov_b32 v[92:93], v[248:249], v[248:249] op_sel:[0,1]
	v_pk_mov_b32 v[94:95], v[250:251], v[250:251] op_sel:[0,1]
	v_pk_mov_b32 v[96:97], v[252:253], v[252:253] op_sel:[0,1]
	v_pk_mov_b32 v[98:99], v[240:241], v[240:241] op_sel:[0,1]
	v_pk_mov_b32 v[100:101], v[186:187], v[186:187] op_sel:[0,1]
	v_mov_b32_e32 v85, v84
	v_mov_b32_e32 v87, v86
	s_and_b64 vcc, exec, s[18:19]
	s_nop 0
	v_lshlrev_b32_e32 v102, 16, v74
	v_and_b32_e32 v103, 0xffff0000, v74
	v_lshlrev_b32_e32 v74, 16, v75
	v_and_b32_e32 v75, 0xffff0000, v75
	v_pk_add_f32 v[74:75], v[74:75], v[84:85] neg_lo:[0,1] neg_hi:[0,1]
	v_pk_add_f32 v[102:103], v[102:103], v[84:85] neg_lo:[0,1] neg_hi:[0,1]
	v_pk_mul_f32 v[74:75], v[86:87], v[74:75]
	v_pk_mul_f32 v[102:103], v[86:87], v[102:103]
	s_nop 0
	v_pk_fma_f32 v[74:75], v[92:93], v[74:75], v[100:101]
	v_pk_fma_f32 v[90:91], v[90:91], v[102:103], v[98:99]
	v_pk_fma_f32 v[72:73], v[74:75], s[86:87], v[72:73] op_sel_hi:[1,0,1]
	v_lshlrev_b32_e32 v74, 16, v76
	v_and_b32_e32 v75, 0xffff0000, v76
	v_pk_add_f32 v[74:75], v[74:75], v[84:85] neg_lo:[0,1] neg_hi:[0,1]
	v_pk_fma_f32 v[70:71], v[90:91], s[86:87], v[70:71] op_sel_hi:[1,0,1]
	v_pk_mul_f32 v[74:75], v[86:87], v[74:75]
	s_nop 0
	v_pk_fma_f32 v[74:75], v[78:79], v[74:75], v[94:95]
	s_nop 0
	v_pk_fma_f32 v[66:67], v[74:75], s[86:87], v[66:67] op_sel_hi:[1,0,1]
	v_lshlrev_b32_e32 v74, 16, v77
	v_and_b32_e32 v75, 0xffff0000, v77
	v_pk_add_f32 v[74:75], v[74:75], v[84:85] neg_lo:[0,1] neg_hi:[0,1]
	s_nop 0
	v_pk_mul_f32 v[74:75], v[86:87], v[74:75]
	s_nop 0
	v_pk_fma_f32 v[74:75], v[80:81], v[74:75], v[96:97]
	s_nop 0
	v_pk_fma_f32 v[68:69], v[74:75], s[86:87], v[68:69] op_sel_hi:[1,0,1]
	s_cbranch_vccnz .LBB0_2038
	global_store_dwordx4 v[88:89], v[70:73], off offset:512
	global_store_dwordx4 v[88:89], v[66:69], off offset:528
	s_cbranch_execnz .LBB0_2005

; DI float bperm(float v, int srclane) { return __int_as_float(__builtin_amdgcn_ds_bpermute(srclane << 2, __float_as_int(v))); }
; DI u32x4 pack8(const float (&v)[8]) { u32x4 w; w.x = pk2(v[0], v[1]); w.y = pk2(v[2], v[3]); w.z = pk2(v[4], v[5]); w.w = pk2(v[6], v[7]); return w; }
; DI void row_stats(const float* STAT, int row, int fq, int lane, float& mu, float& rstd) {
;     const f32x4 a = *(const f32x4*)(STAT + (size_t)row * 32 + fq * 8), b = *(const f32x4*)(STAT + (size_t)row * 32 + fq * 8 + 4);
;     float s = (a[0] + a[2]) + (b[0] + b[2]), q = (a[1] + a[3]) + (b[1] + b[3]);
;     s += bperm(s, lane ^ 16); q += bperm(q, lane ^ 16); s += bperm(s, lane ^ 32); q += bperm(q, lane ^ 32);
;     mu = s * (1.0f / 1024.0f); rstd = __builtin_amdgcn_rsqf(fmaxf(q * (1.0f / 1024.0f) - mu * mu, 0.f) + EPS);
; }
;     DI void operator()(const f32x4 (&acc)[2][2][4][2], const pg8::Unit& u, int wr, int wc, int fr, int fq) const {
;     ...
;             for (int m = 0; m < 4; ++m) { const int row = row0 + ai * 128 + m * 16; const size_t off = (size_t)row * DMODEL + col0; float mu, rstd; row_stats(STAT, row, fq, lane, mu, rstd);
; #pragma unroll
;                 for (int bj = 0; bj < 2; ++bj) { float p[8]; unpack8(*(const u32x4*)(XBin + off + bj * 128), p);
;                     const f32x4 g0 = *(const f32x4*)(g + col0 + bj * 128), g1 = *(const f32x4*)(g + col0 + bj * 128 + 4), b0 = *(const f32x4*)(b + col0 + bj * 128), b1 = *(const f32x4*)(b + col0 + bj * 128 + 4);
;                     float o[8];
; #pragma unroll
;                     for (int k = 0; k < 8; ++k) { const float gg = k < 4 ? g0[k & 3] : g1[k & 3], bb = k < 4 ? b0[k & 3] : b1[k & 3]; const float x1 = (p[k] - mu) * rstd * gg + bb; o[k] = x1 * ALPHA + acc[ai][bj][m][k >> 2][k & 3]; }
;                     if (out32) { *(f32x4*)(out32 + off + bj * 128) = (f32x4){o[0], o[1], o[2], o[3]}; *(f32x4*)(out32 + off + bj * 128 + 4) = (f32x4){o[4], o[5], o[6], o[7]}; }
;                     else *(u32x4*)(XBout + off + bj * 128) = pack8(o); }
.LBB0_2005:
	s_nop 0
	v_add_u32_e32 v66, 0x80, v146
	v_ashrrev_i32_e32 v67, 31, v66
	v_lshlrev_b64 v[68:69], 10, v[66:67]
	v_lshlrev_b64 v[66:67], 7, v[66:67]
	v_lshl_add_u64 v[66:67], s[36:37], 0, v[66:67]
	v_lshl_add_u64 v[70:71], v[144:145], 2, v[66:67]
	v_lshl_add_u64 v[72:73], v[68:69], 0, v[148:149]
	global_load_dwordx4 v[66:69], v[70:71], off offset:16
	global_load_dwordx4 v[74:77], v[70:71], off
	v_lshl_add_u64 v[178:179], v[72:73], 1, s[26:27]
	global_load_dwordx4 v[170:173], v[178:179], off
	global_load_dwordx4 v[174:177], v[178:179], off offset:256
	s_mov_b32 s2, 0x3a800000
	s_and_b64 vcc, exec, s[18:19]
	s_waitcnt vmcnt(3)
	v_pk_add_f32 v[66:67], v[66:67], v[68:69]
	s_waitcnt vmcnt(2)
	v_pk_add_f32 v[70:71], v[74:75], v[76:77]
	s_nop 0
	v_pk_add_f32 v[66:67], v[70:71], v[66:67]
	ds_bpermute_b32 v68, v163, v66
	ds_bpermute_b32 v69, v163, v67
	s_waitcnt lgkmcnt(0)
	v_pk_add_f32 v[66:67], v[66:67], v[68:69]
	ds_bpermute_b32 v68, v162, v66
	ds_bpermute_b32 v69, v162, v67
	s_waitcnt lgkmcnt(0)
	v_pk_add_f32 v[66:67], v[66:67], v[68:69]
	s_nop 0
	v_pk_mul_f32 v[68:69], v[66:67], s[2:3] op_sel_hi:[1,0]
	s_nop 0
	v_fma_f32 v66, -v68, v68, v69
	v_max_f32_e32 v66, 0, v66
	v_add_f32_e32 v66, 0x3727c5ac, v66
	v_rsq_f32_e32 v70, v66
	v_lshl_add_u64 v[66:67], v[72:73], 1, s[26:27]
	s_waitcnt vmcnt(0)
	v_pk_mov_b32 v[74:75], v[170:171], v[170:171] op_sel:[0,1]
	v_pk_mov_b32 v[76:77], v[172:173], v[172:173] op_sel:[0,1]
	s_nop 1
	v_pk_mov_b32 v[78:79], v[220:221], v[220:221] op_sel:[0,1]
	v_pk_mov_b32 v[80:81], v[222:223], v[222:223] op_sel:[0,1]
	v_pk_mov_b32 v[82:83], v[224:225], v[224:225] op_sel:[0,1]
	v_pk_mov_b32 v[84:85], v[226:227], v[226:227] op_sel:[0,1]
	v_pk_mov_b32 v[86:87], v[228:229], v[228:229] op_sel:[0,1]
	v_pk_mov_b32 v[88:89], v[230:231], v[230:231] op_sel:[0,1]
	v_pk_mov_b32 v[90:91], v[232:233], v[232:233] op_sel:[0,1]
	v_pk_mov_b32 v[92:93], v[234:235], v[234:235] op_sel:[0,1]
	v_lshl_add_u64 v[72:73], v[72:73], 2, s[28:29]
	s_waitcnt vmcnt(0)
	v_lshlrev_b32_e32 v94, 16, v74
	v_and_b32_e32 v95, 0xffff0000, v74
	v_lshlrev_b32_e32 v74, 16, v75
	v_and_b32_e32 v75, 0xffff0000, v75
	v_pk_add_f32 v[74:75], v[74:75], v[68:69] op_sel_hi:[1,0] neg_lo:[0,1] neg_hi:[0,1]
	v_pk_add_f32 v[94:95], v[94:95], v[68:69] op_sel_hi:[1,0] neg_lo:[0,1] neg_hi:[0,1]
	v_pk_mul_f32 v[74:75], v[74:75], v[70:71] op_sel_hi:[1,0]
	v_pk_mul_f32 v[94:95], v[94:95], v[70:71] op_sel_hi:[1,0]
	s_waitcnt vmcnt(0)
	v_pk_fma_f32 v[74:75], v[84:85], v[74:75], v[92:93]
	v_pk_fma_f32 v[82:83], v[82:83], v[94:95], v[90:91]
	v_pk_fma_f32 v[64:65], v[74:75], s[86:87], v[64:65] op_sel_hi:[1,0,1]
	v_lshlrev_b32_e32 v74, 16, v76
	v_and_b32_e32 v75, 0xffff0000, v76
	v_pk_add_f32 v[74:75], v[74:75], v[68:69] op_sel_hi:[1,0] neg_lo:[0,1] neg_hi:[0,1]
	v_pk_fma_f32 v[62:63], v[82:83], s[86:87], v[62:63] op_sel_hi:[1,0,1]
	v_pk_mul_f32 v[74:75], v[74:75], v[70:71] op_sel_hi:[1,0]
	s_nop 0
	v_pk_fma_f32 v[74:75], v[78:79], v[74:75], v[86:87]
	s_nop 0
	v_pk_fma_f32 v[58:59], v[74:75], s[86:87], v[58:59] op_sel_hi:[1,0,1]
	v_lshlrev_b32_e32 v74, 16, v77
	v_and_b32_e32 v75, 0xffff0000, v77
	v_pk_add_f32 v[74:75], v[74:75], v[68:69] op_sel_hi:[1,0] neg_lo:[0,1] neg_hi:[0,1]
	s_nop 0
	v_pk_mul_f32 v[74:75], v[74:75], v[70:71] op_sel_hi:[1,0]
	s_nop 0
	v_pk_fma_f32 v[74:75], v[80:81], v[74:75], v[88:89]
	s_nop 0
	v_pk_fma_f32 v[60:61], v[74:75], s[86:87], v[60:61] op_sel_hi:[1,0,1]
	s_cbranch_vccnz .LBB0_2039
	global_store_dwordx4 v[72:73], v[62:65], off
	global_store_dwordx4 v[72:73], v[58:61], off offset:16
	s_cbranch_execnz .LBB0_2008

; DI u32x4 pack8(const float (&v)[8]) { u32x4 w; w.x = pk2(v[0], v[1]); w.y = pk2(v[2], v[3]); w.z = pk2(v[4], v[5]); w.w = pk2(v[6], v[7]); return w; }
;     DI void operator()(const f32x4 (&acc)[2][2][4][2], const pg8::Unit& u, int wr, int wc, int fr, int fq) const {
;     ...
;                 for (int bj = 0; bj < 2; ++bj) { float p[8]; unpack8(*(const u32x4*)(XBin + off + bj * 128), p);
;                     const f32x4 g0 = *(const f32x4*)(g + col0 + bj * 128), g1 = *(const f32x4*)(g + col0 + bj * 128 + 4), b0 = *(const f32x4*)(b + col0 + bj * 128), b1 = *(const f32x4*)(b + col0 + bj * 128 + 4);
;                     float o[8];
; #pragma unroll
;                     for (int k = 0; k < 8; ++k) { const float gg = k < 4 ? g0[k & 3] : g1[k & 3], bb = k < 4 ? b0[k & 3] : b1[k & 3]; const float x1 = (p[k] - mu) * rstd * gg + bb; o[k] = x1 * ALPHA + acc[ai][bj][m][k >> 2][k & 3]; }
;                     if (out32) { *(f32x4*)(out32 + off + bj * 128) = (f32x4){o[0], o[1], o[2], o[3]}; *(f32x4*)(out32 + off + bj * 128 + 4) = (f32x4){o[4], o[5], o[6], o[7]}; }
;                     else *(u32x4*)(XBout + off + bj * 128) = pack8(o); }
.LBB0_2008:
	s_nop 1
	v_pk_mov_b32 v[58:59], v[174:175], v[174:175] op_sel:[0,1]
	v_pk_mov_b32 v[60:61], v[176:177], v[176:177] op_sel:[0,1]
	s_nop 0
	s_nop 1
	v_pk_mov_b32 v[62:63], v[242:243], v[242:243] op_sel:[0,1]
	v_pk_mov_b32 v[64:65], v[244:245], v[244:245] op_sel:[0,1]
	v_pk_mov_b32 v[74:75], v[246:247], v[246:247] op_sel:[0,1]
	v_pk_mov_b32 v[76:77], v[248:249], v[248:249] op_sel:[0,1]
	v_pk_mov_b32 v[78:79], v[250:251], v[250:251] op_sel:[0,1]
	v_pk_mov_b32 v[80:81], v[252:253], v[252:253] op_sel:[0,1]
	v_pk_mov_b32 v[82:83], v[240:241], v[240:241] op_sel:[0,1]
	v_pk_mov_b32 v[84:85], v[186:187], v[186:187] op_sel:[0,1]
	v_mov_b32_e32 v69, v68
	v_mov_b32_e32 v71, v70
	s_and_b64 vcc, exec, s[18:19]
	s_nop 0
	v_lshlrev_b32_e32 v86, 16, v58
	v_and_b32_e32 v87, 0xffff0000, v58
	v_lshlrev_b32_e32 v58, 16, v59
	v_and_b32_e32 v59, 0xffff0000, v59
	v_pk_add_f32 v[58:59], v[58:59], v[68:69] neg_lo:[0,1] neg_hi:[0,1]
	v_pk_add_f32 v[86:87], v[86:87], v[68:69] neg_lo:[0,1] neg_hi:[0,1]
	v_pk_mul_f32 v[58:59], v[70:71], v[58:59]
	v_pk_mul_f32 v[86:87], v[70:71], v[86:87]
	s_nop 0
	v_pk_fma_f32 v[58:59], v[76:77], v[58:59], v[84:85]
	v_pk_fma_f32 v[74:75], v[74:75], v[86:87], v[82:83]
	v_pk_fma_f32 v[56:57], v[58:59], s[86:87], v[56:57] op_sel_hi:[1,0,1]
	v_lshlrev_b32_e32 v58, 16, v60
	v_and_b32_e32 v59, 0xffff0000, v60
	v_pk_add_f32 v[58:59], v[58:59], v[68:69] neg_lo:[0,1] neg_hi:[0,1]
	v_pk_fma_f32 v[54:55], v[74:75], s[86:87], v[54:55] op_sel_hi:[1,0,1]
	v_pk_mul_f32 v[58:59], v[70:71], v[58:59]
	s_nop 0
	v_pk_fma_f32 v[58:59], v[62:63], v[58:59], v[78:79]
	s_nop 0
	v_pk_fma_f32 v[50:51], v[58:59], s[86:87], v[50:51] op_sel_hi:[1,0,1]
	v_lshlrev_b32_e32 v58, 16, v61
	v_and_b32_e32 v59, 0xffff0000, v61
	v_pk_add_f32 v[58:59], v[58:59], v[68:69] neg_lo:[0,1] neg_hi:[0,1]
	s_nop 0
	v_pk_mul_f32 v[58:59], v[70:71], v[58:59]
	s_nop 0
	v_pk_fma_f32 v[58:59], v[64:65], v[58:59], v[80:81]
	s_nop 0
	v_pk_fma_f32 v[52:53], v[58:59], s[86:87], v[52:53] op_sel_hi:[1,0,1]
	s_cbranch_vccnz .LBB0_2040
	global_store_dwordx4 v[72:73], v[54:57], off offset:512
	global_store_dwordx4 v[72:73], v[50:53], off offset:528
	s_cbranch_execnz .LBB0_2011

; DI float bperm(float v, int srclane) { return __int_as_float(__builtin_amdgcn_ds_bpermute(srclane << 2, __float_as_int(v))); }
; DI u32x4 pack8(const float (&v)[8]) { u32x4 w; w.x = pk2(v[0], v[1]); w.y = pk2(v[2], v[3]); w.z = pk2(v[4], v[5]); w.w = pk2(v[6], v[7]); return w; }
; DI void row_stats(const float* STAT, int row, int fq, int lane, float& mu, float& rstd) {
;     const f32x4 a = *(const f32x4*)(STAT + (size_t)row * 32 + fq * 8), b = *(const f32x4*)(STAT + (size_t)row * 32 + fq * 8 + 4);
;     float s = (a[0] + a[2]) + (b[0] + b[2]), q = (a[1] + a[3]) + (b[1] + b[3]);
;     s += bperm(s, lane ^ 16); q += bperm(q, lane ^ 16); s += bperm(s, lane ^ 32); q += bperm(q, lane ^ 32);
;     mu = s * (1.0f / 1024.0f); rstd = __builtin_amdgcn_rsqf(fmaxf(q * (1.0f / 1024.0f) - mu * mu, 0.f) + EPS);
; }
;     DI void operator()(const f32x4 (&acc)[2][2][4][2], const pg8::Unit& u, int wr, int wc, int fr, int fq) const {
;     ...
;             for (int m = 0; m < 4; ++m) { const int row = row0 + ai * 128 + m * 16; const size_t off = (size_t)row * DMODEL + col0; float mu, rstd; row_stats(STAT, row, fq, lane, mu, rstd);
; #pragma unroll
;                 for (int bj = 0; bj < 2; ++bj) { float p[8]; unpack8(*(const u32x4*)(XBin + off + bj * 128), p);
;                     const f32x4 g0 = *(const f32x4*)(g + col0 + bj * 128), g1 = *(const f32x4*)(g + col0 + bj * 128 + 4), b0 = *(const f32x4*)(b + col0 + bj * 128), b1 = *(const f32x4*)(b + col0 + bj * 128 + 4);
;                     float o[8];
; #pragma unroll
;                     for (int k = 0; k < 8; ++k) { const float gg = k < 4 ? g0[k & 3] : g1[k & 3], bb = k < 4 ? b0[k & 3] : b1[k & 3]; const float x1 = (p[k] - mu) * rstd * gg + bb; o[k] = x1 * ALPHA + acc[ai][bj][m][k >> 2][k & 3]; }
;                     if (out32) { *(f32x4*)(out32 + off + bj * 128) = (f32x4){o[0], o[1], o[2], o[3]}; *(f32x4*)(out32 + off + bj * 128 + 4) = (f32x4){o[4], o[5], o[6], o[7]}; }
;                     else *(u32x4*)(XBout + off + bj * 128) = pack8(o); }
.LBB0_2011:
	s_nop 0
	v_add_u32_e32 v50, 0x90, v146
	v_ashrrev_i32_e32 v51, 31, v50
	v_lshlrev_b64 v[52:53], 10, v[50:51]
	v_lshlrev_b64 v[50:51], 7, v[50:51]
	v_lshl_add_u64 v[50:51], s[36:37], 0, v[50:51]
	v_lshl_add_u64 v[54:55], v[144:145], 2, v[50:51]
	s_nop 1
	v_pk_mov_b32 v[58:59], v[220:221], v[220:221] op_sel:[0,1]
	v_pk_mov_b32 v[60:61], v[222:223], v[222:223] op_sel:[0,1]
	v_pk_mov_b32 v[62:63], v[224:225], v[224:225] op_sel:[0,1]
	v_pk_mov_b32 v[64:65], v[226:227], v[226:227] op_sel:[0,1]
	v_pk_mov_b32 v[66:67], v[228:229], v[228:229] op_sel:[0,1]
	v_pk_mov_b32 v[68:69], v[230:231], v[230:231] op_sel:[0,1]
	v_pk_mov_b32 v[70:71], v[232:233], v[232:233] op_sel:[0,1]
	v_pk_mov_b32 v[72:73], v[234:235], v[234:235] op_sel:[0,1]
	v_lshl_add_u64 v[56:57], v[52:53], 0, v[148:149]
	global_load_dwordx4 v[50:53], v[54:55], off offset:16
	global_load_dwordx4 v[74:77], v[54:55], off
	v_lshl_add_u64 v[178:179], v[56:57], 1, s[26:27]
	global_load_dwordx4 v[170:173], v[178:179], off
	global_load_dwordx4 v[174:177], v[178:179], off offset:256
	s_mov_b32 s2, 0x3a800000
	s_and_b64 vcc, exec, s[18:19]
	s_waitcnt vmcnt(3)
	v_pk_add_f32 v[50:51], v[50:51], v[52:53]
	s_waitcnt vmcnt(2)
	v_pk_add_f32 v[54:55], v[74:75], v[76:77]
	s_nop 0
	v_pk_add_f32 v[50:51], v[54:55], v[50:51]
	ds_bpermute_b32 v52, v163, v50
	ds_bpermute_b32 v53, v163, v51
	s_waitcnt lgkmcnt(0)
	v_pk_add_f32 v[50:51], v[50:51], v[52:53]
	ds_bpermute_b32 v52, v162, v50
	ds_bpermute_b32 v53, v162, v51
	s_waitcnt lgkmcnt(0)
	v_pk_add_f32 v[50:51], v[50:51], v[52:53]
	s_nop 0
	v_pk_mul_f32 v[52:53], v[50:51], s[2:3] op_sel_hi:[1,0]
	s_nop 0
	v_fma_f32 v50, -v52, v52, v53
	v_max_f32_e32 v50, 0, v50
	v_add_f32_e32 v50, 0x3727c5ac, v50
	v_rsq_f32_e32 v54, v50
	v_lshl_add_u64 v[50:51], v[56:57], 1, s[26:27]
	s_waitcnt vmcnt(0)
	v_pk_mov_b32 v[74:75], v[170:171], v[170:171] op_sel:[0,1]
	v_pk_mov_b32 v[76:77], v[172:173], v[172:173] op_sel:[0,1]
	v_lshl_add_u64 v[56:57], v[56:57], 2, s[28:29]
	s_waitcnt vmcnt(0)
	v_lshlrev_b32_e32 v78, 16, v74
	v_and_b32_e32 v79, 0xffff0000, v74
	v_pk_add_f32 v[78:79], v[78:79], v[52:53] op_sel_hi:[1,0] neg_lo:[0,1] neg_hi:[0,1]
	s_nop 0
	v_pk_mul_f32 v[78:79], v[78:79], v[54:55] op_sel_hi:[1,0]
	s_nop 0
	v_pk_fma_f32 v[62:63], v[62:63], v[78:79], v[70:71]
	s_nop 0
	v_pk_fma_f32 v[46:47], v[62:63], s[86:87], v[46:47] op_sel_hi:[1,0,1]
	v_lshlrev_b32_e32 v62, 16, v75
	v_and_b32_e32 v63, 0xffff0000, v75
	v_pk_add_f32 v[62:63], v[62:63], v[52:53] op_sel_hi:[1,0] neg_lo:[0,1] neg_hi:[0,1]
	s_nop 0
	v_pk_mul_f32 v[62:63], v[62:63], v[54:55] op_sel_hi:[1,0]
	s_nop 0
	v_pk_fma_f32 v[62:63], v[64:65], v[62:63], v[72:73]
	s_nop 0
	v_pk_fma_f32 v[48:49], v[62:63], s[86:87], v[48:49] op_sel_hi:[1,0,1]
	v_lshlrev_b32_e32 v62, 16, v76
	v_and_b32_e32 v63, 0xffff0000, v76
	v_pk_add_f32 v[62:63], v[62:63], v[52:53] op_sel_hi:[1,0] neg_lo:[0,1] neg_hi:[0,1]
	s_nop 0
	v_pk_mul_f32 v[62:63], v[62:63], v[54:55] op_sel_hi:[1,0]
	s_nop 0
	v_pk_fma_f32 v[58:59], v[58:59], v[62:63], v[66:67]
	s_nop 0
	v_pk_fma_f32 v[42:43], v[58:59], s[86:87], v[42:43] op_sel_hi:[1,0,1]
	v_lshlrev_b32_e32 v58, 16, v77
	v_and_b32_e32 v59, 0xffff0000, v77
	v_pk_add_f32 v[58:59], v[58:59], v[52:53] op_sel_hi:[1,0] neg_lo:[0,1] neg_hi:[0,1]
	s_nop 0
	v_pk_mul_f32 v[58:59], v[58:59], v[54:55] op_sel_hi:[1,0]
	s_nop 0
	v_pk_fma_f32 v[58:59], v[60:61], v[58:59], v[68:69]
	s_nop 0
	v_pk_fma_f32 v[44:45], v[58:59], s[86:87], v[44:45] op_sel_hi:[1,0,1]
	s_cbranch_vccnz .LBB0_2041
	global_store_dwordx4 v[56:57], v[46:49], off
	global_store_dwordx4 v[56:57], v[42:45], off offset:16
	s_cbranch_execnz .LBB0_2014

; DI u32x4 pack8(const float (&v)[8]) { u32x4 w; w.x = pk2(v[0], v[1]); w.y = pk2(v[2], v[3]); w.z = pk2(v[4], v[5]); w.w = pk2(v[6], v[7]); return w; }
;     DI void operator()(const f32x4 (&acc)[2][2][4][2], const pg8::Unit& u, int wr, int wc, int fr, int fq) const {
;     ...
;                 for (int bj = 0; bj < 2; ++bj) { float p[8]; unpack8(*(const u32x4*)(XBin + off + bj * 128), p);
;                     const f32x4 g0 = *(const f32x4*)(g + col0 + bj * 128), g1 = *(const f32x4*)(g + col0 + bj * 128 + 4), b0 = *(const f32x4*)(b + col0 + bj * 128), b1 = *(const f32x4*)(b + col0 + bj * 128 + 4);
;                     float o[8];
; #pragma unroll
;                     for (int k = 0; k < 8; ++k) { const float gg = k < 4 ? g0[k & 3] : g1[k & 3], bb = k < 4 ? b0[k & 3] : b1[k & 3]; const float x1 = (p[k] - mu) * rstd * gg + bb; o[k] = x1 * ALPHA + acc[ai][bj][m][k >> 2][k & 3]; }
;                     if (out32) { *(f32x4*)(out32 + off + bj * 128) = (f32x4){o[0], o[1], o[2], o[3]}; *(f32x4*)(out32 + off + bj * 128 + 4) = (f32x4){o[4], o[5], o[6], o[7]}; }
;                     else *(u32x4*)(XBout + off + bj * 128) = pack8(o); }
.LBB0_2014:
	s_nop 1
	v_pk_mov_b32 v[42:43], v[174:175], v[174:175] op_sel:[0,1]
	v_pk_mov_b32 v[44:45], v[176:177], v[176:177] op_sel:[0,1]
	s_nop 0
	s_nop 1
	v_pk_mov_b32 v[46:47], v[242:243], v[242:243] op_sel:[0,1]
	v_pk_mov_b32 v[48:49], v[244:245], v[244:245] op_sel:[0,1]
	v_pk_mov_b32 v[58:59], v[246:247], v[246:247] op_sel:[0,1]
	v_pk_mov_b32 v[60:61], v[248:249], v[248:249] op_sel:[0,1]
	v_pk_mov_b32 v[62:63], v[250:251], v[250:251] op_sel:[0,1]
	v_pk_mov_b32 v[64:65], v[252:253], v[252:253] op_sel:[0,1]
	v_pk_mov_b32 v[66:67], v[240:241], v[240:241] op_sel:[0,1]
	v_pk_mov_b32 v[68:69], v[186:187], v[186:187] op_sel:[0,1]
	v_mov_b32_e32 v53, v52
	v_mov_b32_e32 v55, v54
	s_and_b64 vcc, exec, s[18:19]
	s_nop 0
	v_lshlrev_b32_e32 v70, 16, v42
	v_and_b32_e32 v71, 0xffff0000, v42
	v_lshlrev_b32_e32 v42, 16, v43
	v_and_b32_e32 v43, 0xffff0000, v43
	v_pk_add_f32 v[42:43], v[42:43], v[52:53] neg_lo:[0,1] neg_hi:[0,1]
	v_pk_add_f32 v[70:71], v[70:71], v[52:53] neg_lo:[0,1] neg_hi:[0,1]
	v_pk_mul_f32 v[42:43], v[54:55], v[42:43]
	v_pk_mul_f32 v[70:71], v[54:55], v[70:71]
	s_nop 0
	v_pk_fma_f32 v[42:43], v[60:61], v[42:43], v[68:69]
	v_pk_fma_f32 v[58:59], v[58:59], v[70:71], v[66:67]
	v_pk_fma_f32 v[40:41], v[42:43], s[86:87], v[40:41] op_sel_hi:[1,0,1]
	v_lshlrev_b32_e32 v42, 16, v44
	v_and_b32_e32 v43, 0xffff0000, v44
	v_pk_add_f32 v[42:43], v[42:43], v[52:53] neg_lo:[0,1] neg_hi:[0,1]
	v_pk_fma_f32 v[38:39], v[58:59], s[86:87], v[38:39] op_sel_hi:[1,0,1]
	v_pk_mul_f32 v[42:43], v[54:55], v[42:43]
	s_nop 0
	v_pk_fma_f32 v[42:43], v[46:47], v[42:43], v[62:63]
	s_nop 0
	v_pk_fma_f32 v[34:35], v[42:43], s[86:87], v[34:35] op_sel_hi:[1,0,1]
	v_lshlrev_b32_e32 v42, 16, v45
	v_and_b32_e32 v43, 0xffff0000, v45
	v_pk_add_f32 v[42:43], v[42:43], v[52:53] neg_lo:[0,1] neg_hi:[0,1]
	s_nop 0
	v_pk_mul_f32 v[42:43], v[54:55], v[42:43]
	s_nop 0
	v_pk_fma_f32 v[42:43], v[48:49], v[42:43], v[64:65]
	s_nop 0
	v_pk_fma_f32 v[36:37], v[42:43], s[86:87], v[36:37] op_sel_hi:[1,0,1]
	s_cbranch_vccnz .LBB0_2042
	global_store_dwordx4 v[56:57], v[38:41], off offset:512
	global_store_dwordx4 v[56:57], v[34:37], off offset:528
	s_cbranch_execnz .LBB0_2017

; DI float bperm(float v, int srclane) { return __int_as_float(__builtin_amdgcn_ds_bpermute(srclane << 2, __float_as_int(v))); }
; DI u32x4 pack8(const float (&v)[8]) { u32x4 w; w.x = pk2(v[0], v[1]); w.y = pk2(v[2], v[3]); w.z = pk2(v[4], v[5]); w.w = pk2(v[6], v[7]); return w; }
; DI void row_stats(const float* STAT, int row, int fq, int lane, float& mu, float& rstd) {
;     const f32x4 a = *(const f32x4*)(STAT + (size_t)row * 32 + fq * 8), b = *(const f32x4*)(STAT + (size_t)row * 32 + fq * 8 + 4);
;     float s = (a[0] + a[2]) + (b[0] + b[2]), q = (a[1] + a[3]) + (b[1] + b[3]);
;     s += bperm(s, lane ^ 16); q += bperm(q, lane ^ 16); s += bperm(s, lane ^ 32); q += bperm(q, lane ^ 32);
;     mu = s * (1.0f / 1024.0f); rstd = __builtin_amdgcn_rsqf(fmaxf(q * (1.0f / 1024.0f) - mu * mu, 0.f) + EPS);
; }
;     DI void operator()(const f32x4 (&acc)[2][2][4][2], const pg8::Unit& u, int wr, int wc, int fr, int fq) const {
;     ...
;             for (int m = 0; m < 4; ++m) { const int row = row0 + ai * 128 + m * 16; const size_t off = (size_t)row * DMODEL + col0; float mu, rstd; row_stats(STAT, row, fq, lane, mu, rstd);
; #pragma unroll
;                 for (int bj = 0; bj < 2; ++bj) { float p[8]; unpack8(*(const u32x4*)(XBin + off + bj * 128), p);
;                     const f32x4 g0 = *(const f32x4*)(g + col0 + bj * 128), g1 = *(const f32x4*)(g + col0 + bj * 128 + 4), b0 = *(const f32x4*)(b + col0 + bj * 128), b1 = *(const f32x4*)(b + col0 + bj * 128 + 4);
;                     float o[8];
; #pragma unroll
;                     for (int k = 0; k < 8; ++k) { const float gg = k < 4 ? g0[k & 3] : g1[k & 3], bb = k < 4 ? b0[k & 3] : b1[k & 3]; const float x1 = (p[k] - mu) * rstd * gg + bb; o[k] = x1 * ALPHA + acc[ai][bj][m][k >> 2][k & 3]; }
;                     if (out32) { *(f32x4*)(out32 + off + bj * 128) = (f32x4){o[0], o[1], o[2], o[3]}; *(f32x4*)(out32 + off + bj * 128 + 4) = (f32x4){o[4], o[5], o[6], o[7]}; }
;                     else *(u32x4*)(XBout + off + bj * 128) = pack8(o); }
.LBB0_2017:
	s_nop 0
	v_add_u32_e32 v34, 0xa0, v146
	v_ashrrev_i32_e32 v35, 31, v34
	v_lshlrev_b64 v[36:37], 10, v[34:35]
	v_lshlrev_b64 v[34:35], 7, v[34:35]
	v_lshl_add_u64 v[34:35], s[36:37], 0, v[34:35]
	v_lshl_add_u64 v[38:39], v[144:145], 2, v[34:35]
	s_nop 1
	v_pk_mov_b32 v[42:43], v[220:221], v[220:221] op_sel:[0,1]
	v_pk_mov_b32 v[44:45], v[222:223], v[222:223] op_sel:[0,1]
	v_pk_mov_b32 v[46:47], v[224:225], v[224:225] op_sel:[0,1]
	v_pk_mov_b32 v[48:49], v[226:227], v[226:227] op_sel:[0,1]
	v_pk_mov_b32 v[50:51], v[228:229], v[228:229] op_sel:[0,1]
	v_pk_mov_b32 v[52:53], v[230:231], v[230:231] op_sel:[0,1]
	v_pk_mov_b32 v[54:55], v[232:233], v[232:233] op_sel:[0,1]
	v_pk_mov_b32 v[56:57], v[234:235], v[234:235] op_sel:[0,1]
	v_lshl_add_u64 v[40:41], v[36:37], 0, v[148:149]
	global_load_dwordx4 v[34:37], v[38:39], off offset:16
	global_load_dwordx4 v[58:61], v[38:39], off
	v_lshl_add_u64 v[178:179], v[40:41], 1, s[26:27]
	global_load_dwordx4 v[170:173], v[178:179], off
	global_load_dwordx4 v[174:177], v[178:179], off offset:256
	s_mov_b32 s2, 0x3a800000
	s_and_b64 vcc, exec, s[18:19]
	s_waitcnt vmcnt(3)
	v_pk_add_f32 v[34:35], v[34:35], v[36:37]
	s_waitcnt vmcnt(2)
	v_pk_add_f32 v[38:39], v[58:59], v[60:61]
	s_nop 0
	v_pk_add_f32 v[34:35], v[38:39], v[34:35]
	ds_bpermute_b32 v36, v163, v34
	ds_bpermute_b32 v37, v163, v35
	s_waitcnt lgkmcnt(0)
	v_pk_add_f32 v[34:35], v[34:35], v[36:37]
	ds_bpermute_b32 v36, v162, v34
	ds_bpermute_b32 v37, v162, v35
	s_waitcnt lgkmcnt(0)
	v_pk_add_f32 v[34:35], v[34:35], v[36:37]
	s_nop 0
	v_pk_mul_f32 v[36:37], v[34:35], s[2:3] op_sel_hi:[1,0]
	s_nop 0
	v_fma_f32 v34, -v36, v36, v37
	v_max_f32_e32 v34, 0, v34
	v_add_f32_e32 v34, 0x3727c5ac, v34
	v_rsq_f32_e32 v38, v34
	v_lshl_add_u64 v[34:35], v[40:41], 1, s[26:27]
	s_waitcnt vmcnt(0)
	v_pk_mov_b32 v[58:59], v[170:171], v[170:171] op_sel:[0,1]
	v_pk_mov_b32 v[60:61], v[172:173], v[172:173] op_sel:[0,1]
	v_lshl_add_u64 v[40:41], v[40:41], 2, s[28:29]
	s_waitcnt vmcnt(0)
	v_lshlrev_b32_e32 v62, 16, v58
	v_and_b32_e32 v63, 0xffff0000, v58
	v_pk_add_f32 v[62:63], v[62:63], v[36:37] op_sel_hi:[1,0] neg_lo:[0,1] neg_hi:[0,1]
	s_nop 0
	v_pk_mul_f32 v[62:63], v[62:63], v[38:39] op_sel_hi:[1,0]
	s_nop 0
	v_pk_fma_f32 v[46:47], v[46:47], v[62:63], v[54:55]
	s_nop 0
	v_pk_fma_f32 v[30:31], v[46:47], s[86:87], v[30:31] op_sel_hi:[1,0,1]
	v_lshlrev_b32_e32 v46, 16, v59
	v_and_b32_e32 v47, 0xffff0000, v59
	v_pk_add_f32 v[46:47], v[46:47], v[36:37] op_sel_hi:[1,0] neg_lo:[0,1] neg_hi:[0,1]
	s_nop 0
	v_pk_mul_f32 v[46:47], v[46:47], v[38:39] op_sel_hi:[1,0]
	s_nop 0
	v_pk_fma_f32 v[46:47], v[48:49], v[46:47], v[56:57]
	s_nop 0
	v_pk_fma_f32 v[32:33], v[46:47], s[86:87], v[32:33] op_sel_hi:[1,0,1]
	v_lshlrev_b32_e32 v46, 16, v60
	v_and_b32_e32 v47, 0xffff0000, v60
	v_pk_add_f32 v[46:47], v[46:47], v[36:37] op_sel_hi:[1,0] neg_lo:[0,1] neg_hi:[0,1]
	s_nop 0
	v_pk_mul_f32 v[46:47], v[46:47], v[38:39] op_sel_hi:[1,0]
	s_nop 0
	v_pk_fma_f32 v[42:43], v[42:43], v[46:47], v[50:51]
	s_nop 0
	v_pk_fma_f32 v[26:27], v[42:43], s[86:87], v[26:27] op_sel_hi:[1,0,1]
	v_lshlrev_b32_e32 v42, 16, v61
	v_and_b32_e32 v43, 0xffff0000, v61
	v_pk_add_f32 v[42:43], v[42:43], v[36:37] op_sel_hi:[1,0] neg_lo:[0,1] neg_hi:[0,1]
	s_nop 0
	v_pk_mul_f32 v[42:43], v[42:43], v[38:39] op_sel_hi:[1,0]
	s_nop 0
	v_pk_fma_f32 v[42:43], v[44:45], v[42:43], v[52:53]
	s_nop 0
	v_pk_fma_f32 v[28:29], v[42:43], s[86:87], v[28:29] op_sel_hi:[1,0,1]
	s_cbranch_vccnz .LBB0_2043
	global_store_dwordx4 v[40:41], v[30:33], off
	global_store_dwordx4 v[40:41], v[26:29], off offset:16
	s_cbranch_execnz .LBB0_2020

; DI u32x4 pack8(const float (&v)[8]) { u32x4 w; w.x = pk2(v[0], v[1]); w.y = pk2(v[2], v[3]); w.z = pk2(v[4], v[5]); w.w = pk2(v[6], v[7]); return w; }
;     DI void operator()(const f32x4 (&acc)[2][2][4][2], const pg8::Unit& u, int wr, int wc, int fr, int fq) const {
;     ...
;                 for (int bj = 0; bj < 2; ++bj) { float p[8]; unpack8(*(const u32x4*)(XBin + off + bj * 128), p);
;                     const f32x4 g0 = *(const f32x4*)(g + col0 + bj * 128), g1 = *(const f32x4*)(g + col0 + bj * 128 + 4), b0 = *(const f32x4*)(b + col0 + bj * 128), b1 = *(const f32x4*)(b + col0 + bj * 128 + 4);
;                     float o[8];
; #pragma unroll
;                     for (int k = 0; k < 8; ++k) { const float gg = k < 4 ? g0[k & 3] : g1[k & 3], bb = k < 4 ? b0[k & 3] : b1[k & 3]; const float x1 = (p[k] - mu) * rstd * gg + bb; o[k] = x1 * ALPHA + acc[ai][bj][m][k >> 2][k & 3]; }
;                     if (out32) { *(f32x4*)(out32 + off + bj * 128) = (f32x4){o[0], o[1], o[2], o[3]}; *(f32x4*)(out32 + off + bj * 128 + 4) = (f32x4){o[4], o[5], o[6], o[7]}; }
;                     else *(u32x4*)(XBout + off + bj * 128) = pack8(o); }
.LBB0_2020:
	s_nop 1
	v_pk_mov_b32 v[26:27], v[174:175], v[174:175] op_sel:[0,1]
	v_pk_mov_b32 v[28:29], v[176:177], v[176:177] op_sel:[0,1]
	s_nop 0
	s_nop 1
	v_pk_mov_b32 v[30:31], v[242:243], v[242:243] op_sel:[0,1]
	v_pk_mov_b32 v[32:33], v[244:245], v[244:245] op_sel:[0,1]
	v_pk_mov_b32 v[42:43], v[246:247], v[246:247] op_sel:[0,1]
	v_pk_mov_b32 v[44:45], v[248:249], v[248:249] op_sel:[0,1]
	v_pk_mov_b32 v[46:47], v[250:251], v[250:251] op_sel:[0,1]
	v_pk_mov_b32 v[48:49], v[252:253], v[252:253] op_sel:[0,1]
	v_pk_mov_b32 v[50:51], v[240:241], v[240:241] op_sel:[0,1]
	v_pk_mov_b32 v[52:53], v[186:187], v[186:187] op_sel:[0,1]
	v_mov_b32_e32 v37, v36
	v_mov_b32_e32 v39, v38
	s_and_b64 vcc, exec, s[18:19]
	s_nop 0
	v_lshlrev_b32_e32 v54, 16, v26
	v_and_b32_e32 v55, 0xffff0000, v26
	v_lshlrev_b32_e32 v26, 16, v27
	v_and_b32_e32 v27, 0xffff0000, v27
	v_pk_add_f32 v[26:27], v[26:27], v[36:37] neg_lo:[0,1] neg_hi:[0,1]
	v_pk_add_f32 v[54:55], v[54:55], v[36:37] neg_lo:[0,1] neg_hi:[0,1]
	v_pk_mul_f32 v[26:27], v[38:39], v[26:27]
	v_pk_mul_f32 v[54:55], v[38:39], v[54:55]
	s_nop 0
	v_pk_fma_f32 v[26:27], v[44:45], v[26:27], v[52:53]
	v_pk_fma_f32 v[42:43], v[42:43], v[54:55], v[50:51]
	v_pk_fma_f32 v[24:25], v[26:27], s[86:87], v[24:25] op_sel_hi:[1,0,1]
	v_lshlrev_b32_e32 v26, 16, v28
	v_and_b32_e32 v27, 0xffff0000, v28
	v_pk_add_f32 v[26:27], v[26:27], v[36:37] neg_lo:[0,1] neg_hi:[0,1]
	v_pk_fma_f32 v[22:23], v[42:43], s[86:87], v[22:23] op_sel_hi:[1,0,1]
	v_pk_mul_f32 v[26:27], v[38:39], v[26:27]
	s_nop 0
	v_pk_fma_f32 v[26:27], v[30:31], v[26:27], v[46:47]
	s_nop 0
	v_pk_fma_f32 v[18:19], v[26:27], s[86:87], v[18:19] op_sel_hi:[1,0,1]
	v_lshlrev_b32_e32 v26, 16, v29
	v_and_b32_e32 v27, 0xffff0000, v29
	v_pk_add_f32 v[26:27], v[26:27], v[36:37] neg_lo:[0,1] neg_hi:[0,1]
	s_nop 0
	v_pk_mul_f32 v[26:27], v[38:39], v[26:27]
	s_nop 0
	v_pk_fma_f32 v[26:27], v[32:33], v[26:27], v[48:49]
	s_nop 0
	v_pk_fma_f32 v[20:21], v[26:27], s[86:87], v[20:21] op_sel_hi:[1,0,1]
	s_cbranch_vccnz .LBB0_2044
	global_store_dwordx4 v[40:41], v[22:25], off offset:512
	global_store_dwordx4 v[40:41], v[18:21], off offset:528
	s_cbranch_execnz .LBB0_2023

; DI float bperm(float v, int srclane) { return __int_as_float(__builtin_amdgcn_ds_bpermute(srclane << 2, __float_as_int(v))); }
; DI u32x4 pack8(const float (&v)[8]) { u32x4 w; w.x = pk2(v[0], v[1]); w.y = pk2(v[2], v[3]); w.z = pk2(v[4], v[5]); w.w = pk2(v[6], v[7]); return w; }
; DI void row_stats(const float* STAT, int row, int fq, int lane, float& mu, float& rstd) {
;     const f32x4 a = *(const f32x4*)(STAT + (size_t)row * 32 + fq * 8), b = *(const f32x4*)(STAT + (size_t)row * 32 + fq * 8 + 4);
;     float s = (a[0] + a[2]) + (b[0] + b[2]), q = (a[1] + a[3]) + (b[1] + b[3]);
;     s += bperm(s, lane ^ 16); q += bperm(q, lane ^ 16); s += bperm(s, lane ^ 32); q += bperm(q, lane ^ 32);
;     mu = s * (1.0f / 1024.0f); rstd = __builtin_amdgcn_rsqf(fmaxf(q * (1.0f / 1024.0f) - mu * mu, 0.f) + EPS);
; }
;     DI void operator()(const f32x4 (&acc)[2][2][4][2], const pg8::Unit& u, int wr, int wc, int fr, int fq) const {
;     ...
;             for (int m = 0; m < 4; ++m) { const int row = row0 + ai * 128 + m * 16; const size_t off = (size_t)row * DMODEL + col0; float mu, rstd; row_stats(STAT, row, fq, lane, mu, rstd);
; #pragma unroll
;                 for (int bj = 0; bj < 2; ++bj) { float p[8]; unpack8(*(const u32x4*)(XBin + off + bj * 128), p);
;                     const f32x4 g0 = *(const f32x4*)(g + col0 + bj * 128), g1 = *(const f32x4*)(g + col0 + bj * 128 + 4), b0 = *(const f32x4*)(b + col0 + bj * 128), b1 = *(const f32x4*)(b + col0 + bj * 128 + 4);
;                     float o[8];
; #pragma unroll
;                     for (int k = 0; k < 8; ++k) { const float gg = k < 4 ? g0[k & 3] : g1[k & 3], bb = k < 4 ? b0[k & 3] : b1[k & 3]; const float x1 = (p[k] - mu) * rstd * gg + bb; o[k] = x1 * ALPHA + acc[ai][bj][m][k >> 2][k & 3]; }
;                     if (out32) { *(f32x4*)(out32 + off + bj * 128) = (f32x4){o[0], o[1], o[2], o[3]}; *(f32x4*)(out32 + off + bj * 128 + 4) = (f32x4){o[4], o[5], o[6], o[7]}; }
;                     else *(u32x4*)(XBout + off + bj * 128) = pack8(o); }
.LBB0_2023:
	s_nop 0
	v_add_u32_e32 v18, 0xb0, v146
	v_ashrrev_i32_e32 v19, 31, v18
	v_lshlrev_b64 v[20:21], 10, v[18:19]
	v_lshlrev_b64 v[18:19], 7, v[18:19]
	v_lshl_add_u64 v[18:19], s[36:37], 0, v[18:19]
	v_lshl_add_u64 v[22:23], v[144:145], 2, v[18:19]
	s_nop 1
	v_pk_mov_b32 v[26:27], v[220:221], v[220:221] op_sel:[0,1]
	v_pk_mov_b32 v[28:29], v[222:223], v[222:223] op_sel:[0,1]
	v_pk_mov_b32 v[30:31], v[224:225], v[224:225] op_sel:[0,1]
	v_pk_mov_b32 v[32:33], v[226:227], v[226:227] op_sel:[0,1]
	v_pk_mov_b32 v[34:35], v[228:229], v[228:229] op_sel:[0,1]
	v_pk_mov_b32 v[36:37], v[230:231], v[230:231] op_sel:[0,1]
	v_pk_mov_b32 v[38:39], v[232:233], v[232:233] op_sel:[0,1]
	v_pk_mov_b32 v[40:41], v[234:235], v[234:235] op_sel:[0,1]
	v_lshl_add_u64 v[24:25], v[20:21], 0, v[148:149]
	global_load_dwordx4 v[18:21], v[22:23], off offset:16
	global_load_dwordx4 v[42:45], v[22:23], off
	v_lshl_add_u64 v[178:179], v[24:25], 1, s[26:27]
	global_load_dwordx4 v[170:173], v[178:179], off
	global_load_dwordx4 v[174:177], v[178:179], off offset:256
	s_mov_b32 s2, 0x3a800000
	s_and_b64 vcc, exec, s[18:19]
	s_waitcnt vmcnt(3)
	v_pk_add_f32 v[18:19], v[18:19], v[20:21]
	s_waitcnt vmcnt(2)
	v_pk_add_f32 v[22:23], v[42:43], v[44:45]
	s_nop 0
	v_pk_add_f32 v[18:19], v[22:23], v[18:19]
	ds_bpermute_b32 v20, v163, v18
	ds_bpermute_b32 v21, v163, v19
	s_waitcnt lgkmcnt(0)
	v_pk_add_f32 v[18:19], v[18:19], v[20:21]
	ds_bpermute_b32 v20, v162, v18
	ds_bpermute_b32 v21, v162, v19
	s_waitcnt lgkmcnt(0)
	v_pk_add_f32 v[18:19], v[18:19], v[20:21]
	s_nop 0
	v_pk_mul_f32 v[20:21], v[18:19], s[2:3] op_sel_hi:[1,0]
	s_nop 0
	v_fma_f32 v18, -v20, v20, v21
	v_max_f32_e32 v18, 0, v18
	v_add_f32_e32 v18, 0x3727c5ac, v18
	v_rsq_f32_e32 v22, v18
	v_lshl_add_u64 v[18:19], v[24:25], 1, s[26:27]
	s_waitcnt vmcnt(0)
	v_pk_mov_b32 v[42:43], v[170:171], v[170:171] op_sel:[0,1]
	v_pk_mov_b32 v[44:45], v[172:173], v[172:173] op_sel:[0,1]
	v_lshl_add_u64 v[24:25], v[24:25], 2, s[28:29]
	s_waitcnt vmcnt(0)
	v_lshlrev_b32_e32 v46, 16, v42
	v_and_b32_e32 v47, 0xffff0000, v42
	v_pk_add_f32 v[46:47], v[46:47], v[20:21] op_sel_hi:[1,0] neg_lo:[0,1] neg_hi:[0,1]
	s_nop 0
	v_pk_mul_f32 v[46:47], v[46:47], v[22:23] op_sel_hi:[1,0]
	s_nop 0
	v_pk_fma_f32 v[30:31], v[30:31], v[46:47], v[38:39]
	s_nop 0
	v_pk_fma_f32 v[14:15], v[30:31], s[86:87], v[14:15] op_sel_hi:[1,0,1]
	v_lshlrev_b32_e32 v30, 16, v43
	v_and_b32_e32 v31, 0xffff0000, v43
	v_pk_add_f32 v[30:31], v[30:31], v[20:21] op_sel_hi:[1,0] neg_lo:[0,1] neg_hi:[0,1]
	s_nop 0
	v_pk_mul_f32 v[30:31], v[30:31], v[22:23] op_sel_hi:[1,0]
	s_nop 0
	v_pk_fma_f32 v[30:31], v[32:33], v[30:31], v[40:41]
	s_nop 0
	v_pk_fma_f32 v[16:17], v[30:31], s[86:87], v[16:17] op_sel_hi:[1,0,1]
	v_lshlrev_b32_e32 v30, 16, v44
	v_and_b32_e32 v31, 0xffff0000, v44
	v_pk_add_f32 v[30:31], v[30:31], v[20:21] op_sel_hi:[1,0] neg_lo:[0,1] neg_hi:[0,1]
	s_nop 0
	v_pk_mul_f32 v[30:31], v[30:31], v[22:23] op_sel_hi:[1,0]
	s_nop 0
	v_pk_fma_f32 v[26:27], v[26:27], v[30:31], v[34:35]
	s_nop 0
	v_pk_fma_f32 v[10:11], v[26:27], s[86:87], v[10:11] op_sel_hi:[1,0,1]
	v_lshlrev_b32_e32 v26, 16, v45
	v_and_b32_e32 v27, 0xffff0000, v45
	v_pk_add_f32 v[26:27], v[26:27], v[20:21] op_sel_hi:[1,0] neg_lo:[0,1] neg_hi:[0,1]
	s_nop 0
	v_pk_mul_f32 v[26:27], v[26:27], v[22:23] op_sel_hi:[1,0]
	s_nop 0
	v_pk_fma_f32 v[26:27], v[28:29], v[26:27], v[36:37]
	s_nop 0
	v_pk_fma_f32 v[12:13], v[26:27], s[86:87], v[12:13] op_sel_hi:[1,0,1]
	s_cbranch_vccnz .LBB0_2045
	global_store_dwordx4 v[24:25], v[14:17], off
	global_store_dwordx4 v[24:25], v[10:13], off offset:16
	s_cbranch_execnz .LBB0_2026

; DI u32x4 pack8(const float (&v)[8]) { u32x4 w; w.x = pk2(v[0], v[1]); w.y = pk2(v[2], v[3]); w.z = pk2(v[4], v[5]); w.w = pk2(v[6], v[7]); return w; }
;     DI void operator()(const f32x4 (&acc)[2][2][4][2], const pg8::Unit& u, int wr, int wc, int fr, int fq) const {
;     ...
;                 for (int bj = 0; bj < 2; ++bj) { float p[8]; unpack8(*(const u32x4*)(XBin + off + bj * 128), p);
;                     const f32x4 g0 = *(const f32x4*)(g + col0 + bj * 128), g1 = *(const f32x4*)(g + col0 + bj * 128 + 4), b0 = *(const f32x4*)(b + col0 + bj * 128), b1 = *(const f32x4*)(b + col0 + bj * 128 + 4);
;                     float o[8];
; #pragma unroll
;                     for (int k = 0; k < 8; ++k) { const float gg = k < 4 ? g0[k & 3] : g1[k & 3], bb = k < 4 ? b0[k & 3] : b1[k & 3]; const float x1 = (p[k] - mu) * rstd * gg + bb; o[k] = x1 * ALPHA + acc[ai][bj][m][k >> 2][k & 3]; }
;                     if (out32) { *(f32x4*)(out32 + off + bj * 128) = (f32x4){o[0], o[1], o[2], o[3]}; *(f32x4*)(out32 + off + bj * 128 + 4) = (f32x4){o[4], o[5], o[6], o[7]}; }
;                     else *(u32x4*)(XBout + off + bj * 128) = pack8(o); }
.LBB0_2026:
	s_nop 1
	v_pk_mov_b32 v[10:11], v[174:175], v[174:175] op_sel:[0,1]
	v_pk_mov_b32 v[12:13], v[176:177], v[176:177] op_sel:[0,1]
	s_nop 0
	s_nop 1
	v_pk_mov_b32 v[14:15], v[242:243], v[242:243] op_sel:[0,1]
	v_pk_mov_b32 v[16:17], v[244:245], v[244:245] op_sel:[0,1]
	v_pk_mov_b32 v[26:27], v[246:247], v[246:247] op_sel:[0,1]
	v_pk_mov_b32 v[28:29], v[248:249], v[248:249] op_sel:[0,1]
	v_pk_mov_b32 v[30:31], v[250:251], v[250:251] op_sel:[0,1]
	v_pk_mov_b32 v[32:33], v[252:253], v[252:253] op_sel:[0,1]
	v_pk_mov_b32 v[34:35], v[240:241], v[240:241] op_sel:[0,1]
	v_pk_mov_b32 v[36:37], v[186:187], v[186:187] op_sel:[0,1]
	v_mov_b32_e32 v21, v20
	v_mov_b32_e32 v23, v22
	s_and_b64 vcc, exec, s[18:19]
	s_nop 0
	v_lshlrev_b32_e32 v38, 16, v10
	v_and_b32_e32 v39, 0xffff0000, v10
	v_lshlrev_b32_e32 v10, 16, v11
	v_and_b32_e32 v11, 0xffff0000, v11
	v_pk_add_f32 v[10:11], v[10:11], v[20:21] neg_lo:[0,1] neg_hi:[0,1]
	v_pk_add_f32 v[38:39], v[38:39], v[20:21] neg_lo:[0,1] neg_hi:[0,1]
	v_pk_mul_f32 v[10:11], v[22:23], v[10:11]
	v_pk_mul_f32 v[38:39], v[22:23], v[38:39]
	s_nop 0
	v_pk_fma_f32 v[10:11], v[28:29], v[10:11], v[36:37]
	v_pk_fma_f32 v[26:27], v[26:27], v[38:39], v[34:35]
	v_pk_fma_f32 v[8:9], v[10:11], s[86:87], v[8:9] op_sel_hi:[1,0,1]
	v_lshlrev_b32_e32 v10, 16, v12
	v_and_b32_e32 v11, 0xffff0000, v12
	v_pk_add_f32 v[10:11], v[10:11], v[20:21] neg_lo:[0,1] neg_hi:[0,1]
	v_pk_fma_f32 v[6:7], v[26:27], s[86:87], v[6:7] op_sel_hi:[1,0,1]
	v_pk_mul_f32 v[10:11], v[22:23], v[10:11]
	s_nop 0
	v_pk_fma_f32 v[10:11], v[14:15], v[10:11], v[30:31]
	s_nop 0
	v_pk_fma_f32 v[2:3], v[10:11], s[86:87], v[2:3] op_sel_hi:[1,0,1]
	v_lshlrev_b32_e32 v10, 16, v13
	v_and_b32_e32 v11, 0xffff0000, v13
	v_pk_add_f32 v[10:11], v[10:11], v[20:21] neg_lo:[0,1] neg_hi:[0,1]
	s_nop 0
	v_pk_mul_f32 v[10:11], v[22:23], v[10:11]
	s_nop 0
	v_pk_fma_f32 v[10:11], v[16:17], v[10:11], v[32:33]
	s_nop 0
	v_pk_fma_f32 v[4:5], v[10:11], s[86:87], v[4:5] op_sel_hi:[1,0,1]
	s_cbranch_vccnz .LBB0_2046
	global_store_dwordx4 v[24:25], v[6:9], off offset:512
	global_store_dwordx4 v[24:25], v[2:5], off offset:528
	s_cbranch_execnz .LBB0_2029
